# Up-projection epilogue: conv weight rows for the first two passes are now requested before the slab-boundary stores (wait no longer drains those stores); otherwise identical to previous measured versi
# baseline (speedup 1.0000x reference)
; __device__ __forceinline__ u32x4 pk8(f32x4 a, f32x4 b) { u32x4 w; w.x = cvt_pk(a[0], a[1]); w.y = cvt_pk(a[2], a[3]); w.z = cvt_pk(b[0], b[1]); w.w = cvt_pk(b[2], b[3]); return w; }
;     template <int GV, int NH> __device__ __forceinline__ void part(f32x4 (&acc)[2][2][4][2], const Unit& u, int wr, int wc, int fr, int fq) const {
;         const int jg = 128 * u.pn + 32 * wc + 8 * fq + 4 * NH;
;         const f32x4 w0 = *(const f32x4*)(cw + GV * DFF + jg), w1 = *(const f32x4*)(cw + NUP + GV * DFF + jg), w2 = *(const f32x4*)(cw + 2 * NUP + GV * DFF + jg), bb = *(const f32x4*)(cb + GV * DFF + jg);
;     __device__ __forceinline__ void operator()(f32x4 (&acc)[2][2][4][2], const Unit& u, int wr, int wc, int fr, int fq) const {
;     ...
;         for (int ai = 0; ai < 2; ++ai) { const int slab = (u.pm * 256 + ai * 128 + wr * 64) >> 6;
; #pragma unroll
;             for (int mm = 0; mm < 2; ++mm) { const int m = mm * 3;
;                 if (m == 0 ? fr < 2 : fr >= 14) { const int idx = m == 0 ? 2 + fr : fr - 14;
; #pragma unroll
;                     for (int gv = 0; gv < 2; ++gv) { const int jg = 128 * u.pn + 32 * wc + 8 * fq;
;                         *(u32x4*)(SIDE + ((unsigned)(slab * 4 + idx)) * NUP + gv * DFF + jg) = pk8(acc[ai][gv][m][0], acc[ai][gv][m][1]);
;                         if (m == 3) { float* o = nullptr;
;                             if (slab < MP / 64) { if ((slab & 127) == 127) o = out + O_CVP + ((unsigned)((l * NBP + (slab >> 7)) * 2 + (fr - 14))) * NUP + gv * DFF + jg; }
;                             else o = out + O_CVS + ((unsigned)((l * NBS + (slab - MP / 64)) * 2 + (fr - 14))) * NUP + gv * DFF + jg;
;                             if (o) { *(f32x4*)o = acc[ai][gv][m][0]; *(f32x4*)(o + 4) = acc[ai][gv][m][1]; } } } } } }
.LBB0_1925:
	s_lshl_b32 s25, s86, 8
	s_add_i32 s79, s25, s61
	v_lshl_or_b32 v158, s16, 7, v195
	v_ashrrev_i32_e32 v159, 31, v158
	v_lshlrev_b64 v[214:215], 2, v[158:159]
	v_lshl_add_u64 v[220:221], s[4:5], 0, v[214:215]
	global_load_dwordx4 v[232:235], v[220:221], off
	v_lshl_add_u64 v[220:221], s[18:19], 0, v[214:215]
	global_load_dwordx4 v[238:241], v[220:221], off
	v_lshl_add_u64 v[220:221], s[52:53], 0, v[214:215]
	global_load_dwordx4 v[242:245], v[220:221], off
	v_lshl_add_u64 v[220:221], s[54:55], 0, v[214:215]
	global_load_dwordx4 v[210:213], v[220:221], off
	v_lshl_add_u64 v[220:221], s[4:5], 0, v[214:215]
	global_load_dwordx4 v[198:201], v[220:221], off offset:16
	v_lshl_add_u64 v[220:221], s[18:19], 0, v[214:215]
	global_load_dwordx4 v[202:205], v[220:221], off offset:16
	v_lshl_add_u64 v[220:221], s[52:53], 0, v[214:215]
	global_load_dwordx4 v[206:209], v[220:221], off offset:16
	s_ashr_i32 s62, s79, 4
	s_and_saveexec_b64 s[16:17], s[8:9]
	s_movk_i32 s44, 0x1600
	s_cbranch_execz .LBB0_1927
	v_or_b32_e32 v0, s62, v190
	v_mul_lo_u32 v0, v0, s44
	v_lshl_add_u64 v[134:135], v[0:1], 1, s[22:23]
	v_cvt_pk_bf16_f32 v130, v126, v127
	v_cvt_pk_bf16_f32 v131, v128, v129
	v_cvt_pk_bf16_f32 v132, v94, v95
	v_cvt_pk_bf16_f32 v133, v96, v97
	v_lshl_add_u64 v[134:135], v[158:159], 1, v[134:135]
	global_store_dwordx4 v[134:135], v[130:133], off
	v_add_co_u32_e32 v134, vcc, 0x1000, v134
	s_nop 0
	v_cvt_pk_bf16_f32 v130, v62, v63
	v_cvt_pk_bf16_f32 v131, v64, v65
	v_cvt_pk_bf16_f32 v132, v34, v35
	v_cvt_pk_bf16_f32 v133, v36, v37
	v_addc_co_u32_e32 v135, vcc, 0, v135, vcc
	global_store_dwordx4 v[134:135], v[130:133], off offset:1536

; __device__ __forceinline__ f32x4 sigm4(f32x4 v) { f32x4 o; o[0] = sigm(v[0]); o[1] = sigm(v[1]); o[2] = sigm(v[2]); o[3] = sigm(v[3]); return o; }
; __device__ __forceinline__ float dppr1(float x) { return __int_as_float(__builtin_amdgcn_mov_dpp(__float_as_int(x), 0x121, 0xf, 0xf, true)); }
; __device__ __forceinline__ float dppr2(float x) { return __int_as_float(__builtin_amdgcn_mov_dpp(__float_as_int(x), 0x122, 0xf, 0xf, true)); }
;     template <int GV, int NH> __device__ __forceinline__ void part(f32x4 (&acc)[2][2][4][2], const Unit& u, int wr, int wc, int fr, int fq) const {
;     ...
;             for (int m = 0; m < 4; ++m) {
;                 const f32x4 x3 = acc[ai][GV][m][NH];
;                 f32x4 c1, c2, x2, x1;
; #pragma unroll
;                 for (int i = 0; i < 4; ++i) { c1[i] = dppr1(x3[i]); c2[i] = dppr2(x3[i]); x2[i] = f1 ? c1[i] : p1[i]; x1[i] = f2 ? c2[i] : p2[i]; }
;                 p1 = c1; p2 = c2;
;                 const f32x4 o = bb + x1 * w0 + x2 * w1 + x3 * w2;
;                 if (GV == 0) acc[ai][0][m][NH] = o * sigm4(o);
.LBB0_1959:
	s_or_b64 exec, exec, s[86:87]
	v_lshlrev_b64 v[160:161], 2, v[158:159]
	v_lshl_add_u64 v[176:177], s[4:5], 0, v[160:161]
	v_lshl_add_u64 v[186:187], s[18:19], 0, v[160:161]
	v_mov_b32_dpp v159, v126 row_ror:2 row_mask:0xf bank_mask:0xf bound_ctrl:1
	v_mov_b32_dpp v171, v127 row_ror:2 row_mask:0xf bank_mask:0xf bound_ctrl:1
	v_mov_b32_dpp v173, v128 row_ror:2 row_mask:0xf bank_mask:0xf bound_ctrl:1
	v_mov_b32_dpp v175, v129 row_ror:2 row_mask:0xf bank_mask:0xf bound_ctrl:1
	v_mov_b32_dpp v0, v126 row_ror:1 row_mask:0xf bank_mask:0xf bound_ctrl:1
	v_mov_b32_dpp v170, v127 row_ror:1 row_mask:0xf bank_mask:0xf bound_ctrl:1
	v_mov_b32_dpp v172, v128 row_ror:1 row_mask:0xf bank_mask:0xf bound_ctrl:1
	v_mov_b32_dpp v174, v129 row_ror:1 row_mask:0xf bank_mask:0xf bound_ctrl:1
	v_cndmask_b32_e64 v164, 0, v159, s[12:13]
	v_cndmask_b32_e64 v165, 0, v171, s[12:13]
	v_cndmask_b32_e64 v168, 0, v173, s[12:13]
	v_cndmask_b32_e64 v169, 0, v175, s[12:13]
	v_cndmask_b32_e64 v162, v0, 0, s[10:11]
	v_cndmask_b32_e64 v163, v170, 0, s[10:11]
	v_cndmask_b32_e64 v166, v172, 0, s[10:11]
	v_cndmask_b32_e64 v167, v174, 0, s[10:11]
	s_waitcnt vmcnt(11)
	v_pk_fma_f32 v[168:169], v[234:235], v[168:169], v[240:241]
	v_pk_fma_f32 v[164:165], v[232:233], v[164:165], v[238:239]
	v_pk_fma_f32 v[166:167], v[244:245], v[166:167], v[168:169]
	v_pk_fma_f32 v[162:163], v[242:243], v[162:163], v[164:165]
	v_pk_fma_f32 v[128:129], v[128:129], v[212:213], v[166:167]
	v_pk_fma_f32 v[162:163], v[126:127], v[210:211], v[162:163]
	v_mul_f32_e32 v164, 0xbfb8aa3b, v128
	v_mul_f32_e32 v126, 0xbfb8aa3b, v162
	v_mul_f32_e32 v127, 0xbfb8aa3b, v163
	v_mul_f32_e32 v165, 0xbfb8aa3b, v129
	v_exp_f32_e32 v126, v126
	v_exp_f32_e32 v127, v127
	v_exp_f32_e32 v164, v164
	v_exp_f32_e32 v165, v165
	v_add_f32_e32 v126, 1.0, v126
	v_add_f32_e32 v166, 1.0, v127
	v_add_f32_e32 v127, 1.0, v164
	v_add_f32_e32 v165, 1.0, v165
	v_rcp_f32_e32 v164, v126
	v_rcp_f32_e32 v126, v127
	v_rcp_f32_e32 v127, v165
	v_rcp_f32_e32 v165, v166
	v_pk_mul_f32 v[126:127], v[128:129], v[126:127]
	v_pk_mul_f32 v[128:129], v[162:163], v[164:165]
	v_mov_b32_dpp v179, v122 row_ror:2 row_mask:0xf bank_mask:0xf bound_ctrl:1
	v_mov_b32_dpp v178, v122 row_ror:1 row_mask:0xf bank_mask:0xf bound_ctrl:1
	v_cndmask_b32_e64 v164, v159, v179, s[12:13]
	v_mov_b32_dpp v159, v123 row_ror:2 row_mask:0xf bank_mask:0xf bound_ctrl:1
	v_cndmask_b32_e64 v162, v178, v0, s[10:11]
	v_mov_b32_dpp v0, v123 row_ror:1 row_mask:0xf bank_mask:0xf bound_ctrl:1
	v_cndmask_b32_e64 v165, v171, v159, s[12:13]
	v_mov_b32_dpp v171, v124 row_ror:2 row_mask:0xf bank_mask:0xf bound_ctrl:1
	v_cndmask_b32_e64 v163, v0, v170, s[10:11]
	v_mov_b32_dpp v170, v124 row_ror:1 row_mask:0xf bank_mask:0xf bound_ctrl:1
	v_cndmask_b32_e64 v168, v173, v171, s[12:13]
	v_mov_b32_dpp v173, v125 row_ror:2 row_mask:0xf bank_mask:0xf bound_ctrl:1
	v_cndmask_b32_e64 v166, v170, v172, s[10:11]
	v_mov_b32_dpp v172, v125 row_ror:1 row_mask:0xf bank_mask:0xf bound_ctrl:1
	v_cndmask_b32_e64 v169, v175, v173, s[12:13]
	v_cndmask_b32_e64 v167, v172, v174, s[10:11]
	v_pk_fma_f32 v[168:169], v[234:235], v[168:169], v[240:241]
	v_pk_fma_f32 v[164:165], v[232:233], v[164:165], v[238:239]
	s_nop 0
	v_pk_fma_f32 v[162:163], v[242:243], v[162:163], v[164:165]
	v_pk_fma_f32 v[164:165], v[244:245], v[166:167], v[168:169]
	v_pk_fma_f32 v[122:123], v[122:123], v[210:211], v[162:163]
	v_pk_fma_f32 v[124:125], v[124:125], v[212:213], v[164:165]
	v_mul_f32_e32 v162, 0xbfb8aa3b, v122
	v_mul_f32_e32 v163, 0xbfb8aa3b, v123
	v_mul_f32_e32 v164, 0xbfb8aa3b, v124
	v_mul_f32_e32 v165, 0xbfb8aa3b, v125
	v_exp_f32_e32 v162, v162
	v_exp_f32_e32 v163, v163
	v_exp_f32_e32 v164, v164
	v_exp_f32_e32 v165, v165
	v_add_f32_e32 v162, 1.0, v162
	v_add_f32_e32 v163, 1.0, v163
	v_add_f32_e32 v164, 1.0, v164
	v_add_f32_e32 v165, 1.0, v165
	v_rcp_f32_e32 v162, v162
	v_rcp_f32_e32 v163, v163
	v_rcp_f32_e32 v164, v164
	v_rcp_f32_e32 v165, v165
	v_pk_mul_f32 v[122:123], v[122:123], v[162:163]
	v_pk_mul_f32 v[124:125], v[124:125], v[164:165]
	v_mov_b32_dpp v175, v118 row_ror:2 row_mask:0xf bank_mask:0xf bound_ctrl:1
	v_mov_b32_dpp v174, v118 row_ror:1 row_mask:0xf bank_mask:0xf bound_ctrl:1
	v_cndmask_b32_e64 v164, v179, v175, s[12:13]
	v_mov_b32_dpp v179, v119 row_ror:2 row_mask:0xf bank_mask:0xf bound_ctrl:1
	v_cndmask_b32_e64 v162, v174, v178, s[10:11]
	v_mov_b32_dpp v178, v119 row_ror:1 row_mask:0xf bank_mask:0xf bound_ctrl:1
	v_cndmask_b32_e64 v165, v159, v179, s[12:13]
	v_mov_b32_dpp v159, v120 row_ror:2 row_mask:0xf bank_mask:0xf bound_ctrl:1
	v_cndmask_b32_e64 v163, v178, v0, s[10:11]
	v_mov_b32_dpp v0, v120 row_ror:1 row_mask:0xf bank_mask:0xf bound_ctrl:1
	v_cndmask_b32_e64 v168, v171, v159, s[12:13]
	v_mov_b32_dpp v171, v121 row_ror:2 row_mask:0xf bank_mask:0xf bound_ctrl:1
	v_cndmask_b32_e64 v166, v0, v170, s[10:11]
	v_mov_b32_dpp v170, v121 row_ror:1 row_mask:0xf bank_mask:0xf bound_ctrl:1
	v_cndmask_b32_e64 v169, v173, v171, s[12:13]
	v_cndmask_b32_e64 v167, v170, v172, s[10:11]
	v_pk_fma_f32 v[168:169], v[234:235], v[168:169], v[240:241]
	v_pk_fma_f32 v[164:165], v[232:233], v[164:165], v[238:239]
	s_nop 0
	v_pk_fma_f32 v[162:163], v[242:243], v[162:163], v[164:165]
	v_pk_fma_f32 v[164:165], v[244:245], v[166:167], v[168:169]
	v_pk_fma_f32 v[118:119], v[118:119], v[210:211], v[162:163]
	v_pk_fma_f32 v[120:121], v[120:121], v[212:213], v[164:165]
	v_mul_f32_e32 v162, 0xbfb8aa3b, v118
	v_mul_f32_e32 v163, 0xbfb8aa3b, v119
	v_mul_f32_e32 v164, 0xbfb8aa3b, v120
	v_mul_f32_e32 v165, 0xbfb8aa3b, v121
	v_exp_f32_e32 v162, v162
	v_exp_f32_e32 v163, v163
	v_exp_f32_e32 v164, v164
	v_exp_f32_e32 v165, v165
; __device__ __forceinline__ f32x4 sigm4(f32x4 v) { f32x4 o; o[0] = sigm(v[0]); o[1] = sigm(v[1]); o[2] = sigm(v[2]); o[3] = sigm(v[3]); return o; }
; __device__ __forceinline__ float dppr1(float x) { return __int_as_float(__builtin_amdgcn_mov_dpp(__float_as_int(x), 0x121, 0xf, 0xf, true)); }
; __device__ __forceinline__ float dppr2(float x) { return __int_as_float(__builtin_amdgcn_mov_dpp(__float_as_int(x), 0x122, 0xf, 0xf, true)); }
;     template <int GV, int NH> __device__ __forceinline__ void part(f32x4 (&acc)[2][2][4][2], const Unit& u, int wr, int wc, int fr, int fq) const {
;     ...
;             for (int m = 0; m < 4; ++m) {
;                 const f32x4 x3 = acc[ai][GV][m][NH];
;                 f32x4 c1, c2, x2, x1;
; #pragma unroll
;                 for (int i = 0; i < 4; ++i) { c1[i] = dppr1(x3[i]); c2[i] = dppr2(x3[i]); x2[i] = f1 ? c1[i] : p1[i]; x1[i] = f2 ? c2[i] : p2[i]; }
;                 p1 = c1; p2 = c2;
;                 const f32x4 o = bb + x1 * w0 + x2 * w1 + x3 * w2;
;                 if (GV == 0) acc[ai][0][m][NH] = o * sigm4(o);
	v_add_f32_e32 v162, 1.0, v162
	v_add_f32_e32 v163, 1.0, v163
	v_add_f32_e32 v164, 1.0, v164
	v_add_f32_e32 v165, 1.0, v165
	v_rcp_f32_e32 v162, v162
	v_rcp_f32_e32 v163, v163
	v_rcp_f32_e32 v164, v164
	v_rcp_f32_e32 v165, v165
	v_pk_mul_f32 v[118:119], v[118:119], v[162:163]
	v_pk_mul_f32 v[120:121], v[120:121], v[164:165]
	v_mov_b32_dpp v163, v114 row_ror:2 row_mask:0xf bank_mask:0xf bound_ctrl:1
	v_mov_b32_dpp v165, v115 row_ror:2 row_mask:0xf bank_mask:0xf bound_ctrl:1
	v_mov_b32_dpp v162, v114 row_ror:1 row_mask:0xf bank_mask:0xf bound_ctrl:1
	v_cndmask_b32_e64 v164, v175, v163, s[12:13]
	v_mov_b32_dpp v163, v115 row_ror:1 row_mask:0xf bank_mask:0xf bound_ctrl:1
	v_cndmask_b32_e64 v165, v179, v165, s[12:13]
	v_cndmask_b32_e64 v162, v162, v174, s[10:11]
	v_cndmask_b32_e64 v163, v163, v178, s[10:11]
	v_pk_fma_f32 v[164:165], v[232:233], v[164:165], v[238:239]
	v_mov_b32_dpp v166, v116 row_ror:1 row_mask:0xf bank_mask:0xf bound_ctrl:1
	v_pk_fma_f32 v[162:163], v[242:243], v[162:163], v[164:165]
	v_mov_b32_dpp v167, v116 row_ror:2 row_mask:0xf bank_mask:0xf bound_ctrl:1
	v_cndmask_b32_e64 v166, v166, v0, s[10:11]
	v_mov_b32_dpp v0, v117 row_ror:1 row_mask:0xf bank_mask:0xf bound_ctrl:1
	v_pk_fma_f32 v[114:115], v[114:115], v[210:211], v[162:163]
	v_cndmask_b32_e64 v168, v159, v167, s[12:13]
	v_mov_b32_dpp v159, v117 row_ror:2 row_mask:0xf bank_mask:0xf bound_ctrl:1
	v_cndmask_b32_e64 v167, v0, v170, s[10:11]
	v_mul_f32_e32 v0, 0xbfb8aa3b, v114
	v_cndmask_b32_e64 v169, v171, v159, s[12:13]
	v_exp_f32_e32 v0, v0
	v_mul_f32_e32 v159, 0xbfb8aa3b, v115
	v_pk_fma_f32 v[168:169], v[234:235], v[168:169], v[240:241]
	v_exp_f32_e32 v159, v159
	v_pk_fma_f32 v[164:165], v[244:245], v[166:167], v[168:169]
	v_add_f32_e32 v0, 1.0, v0
	v_pk_fma_f32 v[162:163], v[116:117], v[212:213], v[164:165]
	v_rcp_f32_e32 v116, v0
	v_mul_f32_e32 v117, 0xbfb8aa3b, v162
	v_add_f32_e32 v0, 1.0, v159
	v_exp_f32_e32 v159, v117
	v_mul_f32_e32 v117, 0xbfb8aa3b, v163
	v_exp_f32_e32 v165, v117
	v_rcp_f32_e32 v117, v0
	v_add_f32_e32 v0, 1.0, v159
	v_rcp_f32_e32 v164, v0
	v_add_f32_e32 v0, 1.0, v165
	v_rcp_f32_e32 v165, v0
	v_pk_mul_f32 v[116:117], v[114:115], v[116:117]
	v_pk_mul_f32 v[162:163], v[162:163], v[164:165]
	v_mov_b32_dpp v159, v110 row_ror:2 row_mask:0xf bank_mask:0xf bound_ctrl:1
	v_mov_b32_dpp v171, v111 row_ror:2 row_mask:0xf bank_mask:0xf bound_ctrl:1
	v_mov_b32_dpp v0, v110 row_ror:1 row_mask:0xf bank_mask:0xf bound_ctrl:1
	v_cndmask_b32_e64 v164, 0, v159, s[12:13]
	v_mov_b32_dpp v170, v111 row_ror:1 row_mask:0xf bank_mask:0xf bound_ctrl:1
	v_cndmask_b32_e64 v165, 0, v171, s[12:13]
	v_cndmask_b32_e64 v114, v0, 0, s[10:11]
	v_cndmask_b32_e64 v115, v170, 0, s[10:11]
	v_pk_fma_f32 v[164:165], v[232:233], v[164:165], v[238:239]
	v_mov_b32_dpp v173, v112 row_ror:2 row_mask:0xf bank_mask:0xf bound_ctrl:1
	v_pk_fma_f32 v[114:115], v[242:243], v[114:115], v[164:165]
	v_mov_b32_dpp v175, v113 row_ror:2 row_mask:0xf bank_mask:0xf bound_ctrl:1
	v_pk_fma_f32 v[110:111], v[110:111], v[210:211], v[114:115]
	v_mov_b32_dpp v172, v112 row_ror:1 row_mask:0xf bank_mask:0xf bound_ctrl:1
	v_mul_f32_e32 v114, 0xbfb8aa3b, v110
	v_cndmask_b32_e64 v168, 0, v173, s[12:13]
	v_mov_b32_dpp v174, v113 row_ror:1 row_mask:0xf bank_mask:0xf bound_ctrl:1
	v_cndmask_b32_e64 v169, 0, v175, s[12:13]
	v_exp_f32_e32 v164, v114
	v_cndmask_b32_e64 v166, v172, 0, s[10:11]
	v_cndmask_b32_e64 v167, v174, 0, s[10:11]
	v_pk_fma_f32 v[114:115], v[234:235], v[168:169], v[240:241]
	s_nop 0
	v_pk_fma_f32 v[114:115], v[244:245], v[166:167], v[114:115]
	s_nop 0
	v_pk_fma_f32 v[112:113], v[112:113], v[212:213], v[114:115]
	v_add_f32_e32 v114, 1.0, v164
	v_mul_f32_e32 v115, 0xbfb8aa3b, v111
	v_mul_f32_e32 v164, 0xbfb8aa3b, v112
	v_mul_f32_e32 v165, 0xbfb8aa3b, v113
	v_exp_f32_e32 v115, v115
	v_exp_f32_e32 v164, v164
	v_exp_f32_e32 v165, v165
	v_rcp_f32_e32 v114, v114
	v_add_f32_e32 v115, 1.0, v115
	v_add_f32_e32 v164, 1.0, v164
	v_add_f32_e32 v165, 1.0, v165
	v_rcp_f32_e32 v164, v164
	v_rcp_f32_e32 v165, v165
	v_rcp_f32_e32 v115, v115
	v_pk_mul_f32 v[164:165], v[112:113], v[164:165]
	v_pk_mul_f32 v[166:167], v[110:111], v[114:115]
	v_mov_b32_dpp v179, v106 row_ror:2 row_mask:0xf bank_mask:0xf bound_ctrl:1
	v_mov_b32_dpp v181, v108 row_ror:2 row_mask:0xf bank_mask:0xf bound_ctrl:1
	v_mov_b32_dpp v178, v106 row_ror:1 row_mask:0xf bank_mask:0xf bound_ctrl:1
	v_cndmask_b32_e64 v112, v159, v179, s[12:13]
	v_mov_b32_dpp v159, v107 row_ror:2 row_mask:0xf bank_mask:0xf bound_ctrl:1
	v_mov_b32_dpp v180, v108 row_ror:1 row_mask:0xf bank_mask:0xf bound_ctrl:1
	v_cndmask_b32_e64 v168, v173, v181, s[12:13]
	v_mov_b32_dpp v173, v109 row_ror:2 row_mask:0xf bank_mask:0xf bound_ctrl:1
	v_cndmask_b32_e64 v110, v178, v0, s[10:11]
	v_mov_b32_dpp v0, v107 row_ror:1 row_mask:0xf bank_mask:0xf bound_ctrl:1
	v_cndmask_b32_e64 v113, v171, v159, s[12:13]
	v_cndmask_b32_e64 v114, v180, v172, s[10:11]
	v_mov_b32_dpp v172, v109 row_ror:1 row_mask:0xf bank_mask:0xf bound_ctrl:1
	v_cndmask_b32_e64 v169, v175, v173, s[12:13]
	v_cndmask_b32_e64 v111, v0, v170, s[10:11]
	v_cndmask_b32_e64 v115, v172, v174, s[10:11]
	v_pk_fma_f32 v[168:169], v[234:235], v[168:169], v[240:241]
	v_pk_fma_f32 v[112:113], v[232:233], v[112:113], v[238:239]
	s_nop 0
	v_pk_fma_f32 v[110:111], v[242:243], v[110:111], v[112:113]
	v_pk_fma_f32 v[112:113], v[244:245], v[114:115], v[168:169]
	v_pk_fma_f32 v[106:107], v[106:107], v[210:211], v[110:111]
	v_pk_fma_f32 v[108:109], v[108:109], v[212:213], v[112:113]
	v_mul_f32_e32 v110, 0xbfb8aa3b, v106
	v_mul_f32_e32 v111, 0xbfb8aa3b, v107
	v_mul_f32_e32 v112, 0xbfb8aa3b, v108
	v_mul_f32_e32 v113, 0xbfb8aa3b, v109
; __device__ __forceinline__ f32x4 sigm4(f32x4 v) { f32x4 o; o[0] = sigm(v[0]); o[1] = sigm(v[1]); o[2] = sigm(v[2]); o[3] = sigm(v[3]); return o; }
; __device__ __forceinline__ float dppr1(float x) { return __int_as_float(__builtin_amdgcn_mov_dpp(__float_as_int(x), 0x121, 0xf, 0xf, true)); }
; __device__ __forceinline__ float dppr2(float x) { return __int_as_float(__builtin_amdgcn_mov_dpp(__float_as_int(x), 0x122, 0xf, 0xf, true)); }
;     template <int GV, int NH> __device__ __forceinline__ void part(f32x4 (&acc)[2][2][4][2], const Unit& u, int wr, int wc, int fr, int fq) const {
;     ...
;         const f32x4 w0 = *(const f32x4*)(cw + GV * DFF + jg), w1 = *(const f32x4*)(cw + NUP + GV * DFF + jg), w2 = *(const f32x4*)(cw + 2 * NUP + GV * DFF + jg), bb = *(const f32x4*)(cb + GV * DFF + jg);
;     ...
;             for (int m = 0; m < 4; ++m) {
;                 const f32x4 x3 = acc[ai][GV][m][NH];
;                 f32x4 c1, c2, x2, x1;
; #pragma unroll
;                 for (int i = 0; i < 4; ++i) { c1[i] = dppr1(x3[i]); c2[i] = dppr2(x3[i]); x2[i] = f1 ? c1[i] : p1[i]; x1[i] = f2 ? c2[i] : p2[i]; }
;                 p1 = c1; p2 = c2;
;                 const f32x4 o = bb + x1 * w0 + x2 * w1 + x3 * w2;
;                 if (GV == 0) acc[ai][0][m][NH] = o * sigm4(o);
	v_exp_f32_e32 v110, v110
	v_exp_f32_e32 v111, v111
	v_exp_f32_e32 v112, v112
	v_exp_f32_e32 v113, v113
	v_add_f32_e32 v110, 1.0, v110
	v_add_f32_e32 v111, 1.0, v111
	v_add_f32_e32 v112, 1.0, v112
	v_add_f32_e32 v113, 1.0, v113
	v_rcp_f32_e32 v110, v110
	v_rcp_f32_e32 v111, v111
	v_rcp_f32_e32 v112, v112
	v_rcp_f32_e32 v113, v113
	v_pk_mul_f32 v[168:169], v[106:107], v[110:111]
	v_pk_mul_f32 v[170:171], v[108:109], v[112:113]
	v_mov_b32_dpp v115, v102 row_ror:2 row_mask:0xf bank_mask:0xf bound_ctrl:1
	v_mov_b32_dpp v114, v102 row_ror:1 row_mask:0xf bank_mask:0xf bound_ctrl:1
	v_cndmask_b32_e64 v108, v179, v115, s[12:13]
	v_mov_b32_dpp v179, v103 row_ror:2 row_mask:0xf bank_mask:0xf bound_ctrl:1
	v_cndmask_b32_e64 v106, v114, v178, s[10:11]
	v_mov_b32_dpp v178, v103 row_ror:1 row_mask:0xf bank_mask:0xf bound_ctrl:1
	v_cndmask_b32_e64 v109, v159, v179, s[12:13]
	v_mov_b32_dpp v159, v104 row_ror:2 row_mask:0xf bank_mask:0xf bound_ctrl:1
	v_cndmask_b32_e64 v107, v178, v0, s[10:11]
	v_mov_b32_dpp v0, v104 row_ror:1 row_mask:0xf bank_mask:0xf bound_ctrl:1
	v_cndmask_b32_e64 v112, v181, v159, s[12:13]
	v_mov_b32_dpp v181, v105 row_ror:2 row_mask:0xf bank_mask:0xf bound_ctrl:1
	v_cndmask_b32_e64 v110, v0, v180, s[10:11]
	v_mov_b32_dpp v180, v105 row_ror:1 row_mask:0xf bank_mask:0xf bound_ctrl:1
	v_cndmask_b32_e64 v113, v173, v181, s[12:13]
	v_cndmask_b32_e64 v111, v180, v172, s[10:11]
	v_pk_fma_f32 v[112:113], v[234:235], v[112:113], v[240:241]
	v_pk_fma_f32 v[108:109], v[232:233], v[108:109], v[238:239]
	s_nop 0
	v_pk_fma_f32 v[106:107], v[242:243], v[106:107], v[108:109]
	v_pk_fma_f32 v[108:109], v[244:245], v[110:111], v[112:113]
	v_pk_fma_f32 v[102:103], v[102:103], v[210:211], v[106:107]
	v_pk_fma_f32 v[104:105], v[104:105], v[212:213], v[108:109]
	v_mul_f32_e32 v106, 0xbfb8aa3b, v102
	v_mul_f32_e32 v107, 0xbfb8aa3b, v103
	v_mul_f32_e32 v108, 0xbfb8aa3b, v104
	v_mul_f32_e32 v109, 0xbfb8aa3b, v105
	v_exp_f32_e32 v106, v106
	v_exp_f32_e32 v107, v107
	v_exp_f32_e32 v108, v108
	v_exp_f32_e32 v109, v109
	v_add_f32_e32 v106, 1.0, v106
	v_add_f32_e32 v107, 1.0, v107
	v_add_f32_e32 v108, 1.0, v108
	v_add_f32_e32 v109, 1.0, v109
	v_rcp_f32_e32 v106, v106
	v_rcp_f32_e32 v107, v107
	v_rcp_f32_e32 v108, v108
	v_rcp_f32_e32 v109, v109
	v_pk_mul_f32 v[172:173], v[102:103], v[106:107]
	v_pk_mul_f32 v[174:175], v[104:105], v[108:109]
	v_mov_b32_dpp v103, v98 row_ror:2 row_mask:0xf bank_mask:0xf bound_ctrl:1
	v_mov_b32_dpp v105, v99 row_ror:2 row_mask:0xf bank_mask:0xf bound_ctrl:1
	v_mov_b32_dpp v102, v98 row_ror:1 row_mask:0xf bank_mask:0xf bound_ctrl:1
	v_cndmask_b32_e64 v104, v115, v103, s[12:13]
	v_mov_b32_dpp v103, v99 row_ror:1 row_mask:0xf bank_mask:0xf bound_ctrl:1
	v_cndmask_b32_e64 v105, v179, v105, s[12:13]
	v_cndmask_b32_e64 v102, v102, v114, s[10:11]
	v_cndmask_b32_e64 v103, v103, v178, s[10:11]
	v_pk_fma_f32 v[104:105], v[232:233], v[104:105], v[238:239]
	v_mov_b32_dpp v106, v100 row_ror:1 row_mask:0xf bank_mask:0xf bound_ctrl:1
	v_pk_fma_f32 v[102:103], v[242:243], v[102:103], v[104:105]
	v_mov_b32_dpp v107, v100 row_ror:2 row_mask:0xf bank_mask:0xf bound_ctrl:1
	v_cndmask_b32_e64 v106, v106, v0, s[10:11]
	v_mov_b32_dpp v0, v101 row_ror:1 row_mask:0xf bank_mask:0xf bound_ctrl:1
	v_pk_fma_f32 v[98:99], v[98:99], v[210:211], v[102:103]
	v_cndmask_b32_e64 v108, v159, v107, s[12:13]
	v_cndmask_b32_e64 v107, v0, v180, s[10:11]
	v_mul_f32_e32 v0, 0xbfb8aa3b, v98
	v_mov_b32_dpp v109, v101 row_ror:2 row_mask:0xf bank_mask:0xf bound_ctrl:1
	v_exp_f32_e32 v0, v0
	v_mul_f32_e32 v102, 0xbfb8aa3b, v99
	v_cndmask_b32_e64 v109, v181, v109, s[12:13]
	v_exp_f32_e32 v103, v102
	v_pk_fma_f32 v[108:109], v[234:235], v[108:109], v[240:241]
	v_add_f32_e32 v0, 1.0, v0
	v_pk_fma_f32 v[104:105], v[244:245], v[106:107], v[108:109]
	v_rcp_f32_e32 v102, v0
	v_pk_fma_f32 v[100:101], v[100:101], v[212:213], v[104:105]
	v_add_f32_e32 v0, 1.0, v103
	v_mul_f32_e32 v103, 0xbfb8aa3b, v100
	v_exp_f32_e32 v104, v103
	v_mul_f32_e32 v103, 0xbfb8aa3b, v101
	v_exp_f32_e32 v105, v103
	v_rcp_f32_e32 v103, v0
	v_add_f32_e32 v0, 1.0, v104
	v_rcp_f32_e32 v104, v0
	v_add_f32_e32 v0, 1.0, v105
	v_rcp_f32_e32 v105, v0
	v_pk_mul_f32 v[132:133], v[98:99], v[102:103]
	v_pk_mul_f32 v[134:135], v[100:101], v[104:105]
	v_or_b32_e32 v114, 4, v158
	v_ashrrev_i32_e32 v115, 31, v114
	v_lshlrev_b64 v[130:131], 2, v[114:115]
	v_lshl_add_u64 v[220:221], s[54:55], 0, v[130:131]
	global_load_dwordx4 v[232:235], v[220:221], off
	v_mov_b32_dpp v115, v94 row_ror:2 row_mask:0xf bank_mask:0xf bound_ctrl:1
	v_mov_b32_dpp v145, v95 row_ror:2 row_mask:0xf bank_mask:0xf bound_ctrl:1
	v_mov_b32_dpp v176, v96 row_ror:2 row_mask:0xf bank_mask:0xf bound_ctrl:1
	v_mov_b32_dpp v178, v97 row_ror:2 row_mask:0xf bank_mask:0xf bound_ctrl:1
	v_mov_b32_dpp v0, v94 row_ror:1 row_mask:0xf bank_mask:0xf bound_ctrl:1
	v_mov_b32_dpp v144, v95 row_ror:1 row_mask:0xf bank_mask:0xf bound_ctrl:1
	v_mov_b32_dpp v159, v96 row_ror:1 row_mask:0xf bank_mask:0xf bound_ctrl:1
	v_mov_b32_dpp v177, v97 row_ror:1 row_mask:0xf bank_mask:0xf bound_ctrl:1
	v_cndmask_b32_e64 v138, 0, v115, s[12:13]
	v_cndmask_b32_e64 v139, 0, v145, s[12:13]
	v_cndmask_b32_e64 v142, 0, v176, s[12:13]
	v_cndmask_b32_e64 v143, 0, v178, s[12:13]
	v_cndmask_b32_e64 v136, v0, 0, s[10:11]
	v_cndmask_b32_e64 v137, v144, 0, s[10:11]
	v_cndmask_b32_e64 v140, v159, 0, s[10:11]
	v_cndmask_b32_e64 v141, v177, 0, s[10:11]
	s_waitcnt vmcnt(2)
	v_pk_fma_f32 v[142:143], v[200:201], v[142:143], v[204:205]
	v_pk_fma_f32 v[138:139], v[198:199], v[138:139], v[202:203]
	s_waitcnt vmcnt(1)
	v_pk_fma_f32 v[136:137], v[206:207], v[136:137], v[138:139]
	v_pk_fma_f32 v[138:139], v[208:209], v[140:141], v[142:143]
	s_waitcnt vmcnt(0)
; __device__ __forceinline__ f32x4 sigm4(f32x4 v) { f32x4 o; o[0] = sigm(v[0]); o[1] = sigm(v[1]); o[2] = sigm(v[2]); o[3] = sigm(v[3]); return o; }
; __device__ __forceinline__ float dppr1(float x) { return __int_as_float(__builtin_amdgcn_mov_dpp(__float_as_int(x), 0x121, 0xf, 0xf, true)); }
; __device__ __forceinline__ float dppr2(float x) { return __int_as_float(__builtin_amdgcn_mov_dpp(__float_as_int(x), 0x122, 0xf, 0xf, true)); }
;     template <int GV, int NH> __device__ __forceinline__ void part(f32x4 (&acc)[2][2][4][2], const Unit& u, int wr, int wc, int fr, int fq) const {
;     ...
;             for (int m = 0; m < 4; ++m) {
;                 const f32x4 x3 = acc[ai][GV][m][NH];
;                 f32x4 c1, c2, x2, x1;
; #pragma unroll
;                 for (int i = 0; i < 4; ++i) { c1[i] = dppr1(x3[i]); c2[i] = dppr2(x3[i]); x2[i] = f1 ? c1[i] : p1[i]; x1[i] = f2 ? c2[i] : p2[i]; }
;                 p1 = c1; p2 = c2;
;                 const f32x4 o = bb + x1 * w0 + x2 * w1 + x3 * w2;
;                 if (GV == 0) acc[ai][0][m][NH] = o * sigm4(o);
	v_pk_fma_f32 v[94:95], v[94:95], v[232:233], v[136:137]
	v_pk_fma_f32 v[96:97], v[96:97], v[234:235], v[138:139]
	v_mul_f32_e32 v136, 0xbfb8aa3b, v94
	v_mul_f32_e32 v137, 0xbfb8aa3b, v95
	v_mul_f32_e32 v138, 0xbfb8aa3b, v96
	v_mul_f32_e32 v139, 0xbfb8aa3b, v97
	v_exp_f32_e32 v136, v136
	v_exp_f32_e32 v137, v137
	v_exp_f32_e32 v138, v138
	v_exp_f32_e32 v139, v139
	v_add_f32_e32 v136, 1.0, v136
	v_add_f32_e32 v137, 1.0, v137
	v_add_f32_e32 v138, 1.0, v138
	v_add_f32_e32 v139, 1.0, v139
	v_rcp_f32_e32 v136, v136
	v_rcp_f32_e32 v137, v137
	v_rcp_f32_e32 v138, v138
	v_rcp_f32_e32 v139, v139
	v_pk_mul_f32 v[94:95], v[94:95], v[136:137]
	v_pk_mul_f32 v[96:97], v[96:97], v[138:139]
	v_mov_b32_dpp v180, v90 row_ror:2 row_mask:0xf bank_mask:0xf bound_ctrl:1
	v_mov_b32_dpp v179, v90 row_ror:1 row_mask:0xf bank_mask:0xf bound_ctrl:1
	v_cndmask_b32_e64 v138, v115, v180, s[12:13]
	v_mov_b32_dpp v115, v91 row_ror:2 row_mask:0xf bank_mask:0xf bound_ctrl:1
	v_cndmask_b32_e64 v136, v179, v0, s[10:11]
	v_mov_b32_dpp v0, v91 row_ror:1 row_mask:0xf bank_mask:0xf bound_ctrl:1
	v_cndmask_b32_e64 v139, v145, v115, s[12:13]
	v_cndmask_b32_e64 v137, v0, v144, s[10:11]
	v_pk_fma_f32 v[138:139], v[198:199], v[138:139], v[202:203]
	v_mov_b32_dpp v145, v92 row_ror:2 row_mask:0xf bank_mask:0xf bound_ctrl:1
	v_pk_fma_f32 v[136:137], v[206:207], v[136:137], v[138:139]
	v_mov_b32_dpp v144, v92 row_ror:1 row_mask:0xf bank_mask:0xf bound_ctrl:1
	v_pk_fma_f32 v[136:137], v[90:91], v[232:233], v[136:137]
	v_cndmask_b32_e64 v142, v176, v145, s[12:13]
	v_mov_b32_dpp v176, v93 row_ror:2 row_mask:0xf bank_mask:0xf bound_ctrl:1
	v_mul_f32_e32 v90, 0xbfb8aa3b, v136
	v_cndmask_b32_e64 v140, v144, v159, s[10:11]
	v_mov_b32_dpp v159, v93 row_ror:1 row_mask:0xf bank_mask:0xf bound_ctrl:1
	v_cndmask_b32_e64 v143, v178, v176, s[12:13]
	v_exp_f32_e32 v138, v90
	v_cndmask_b32_e64 v141, v159, v177, s[10:11]
	v_pk_fma_f32 v[90:91], v[200:201], v[142:143], v[204:205]
	s_nop 0
	v_pk_fma_f32 v[90:91], v[208:209], v[140:141], v[90:91]
	s_nop 0
	v_pk_fma_f32 v[90:91], v[92:93], v[234:235], v[90:91]
	v_add_f32_e32 v92, 1.0, v138
	v_mul_f32_e32 v93, 0xbfb8aa3b, v137
	v_mul_f32_e32 v138, 0xbfb8aa3b, v90
	v_mul_f32_e32 v139, 0xbfb8aa3b, v91
	v_exp_f32_e32 v93, v93
	v_exp_f32_e32 v138, v138
	v_exp_f32_e32 v139, v139
	v_rcp_f32_e32 v92, v92
	v_add_f32_e32 v93, 1.0, v93
	v_add_f32_e32 v138, 1.0, v138
	v_add_f32_e32 v139, 1.0, v139
	v_rcp_f32_e32 v138, v138
	v_rcp_f32_e32 v139, v139
	v_rcp_f32_e32 v93, v93
	v_pk_mul_f32 v[90:91], v[90:91], v[138:139]
	v_pk_mul_f32 v[92:93], v[136:137], v[92:93]
	v_mov_b32_dpp v178, v86 row_ror:2 row_mask:0xf bank_mask:0xf bound_ctrl:1
	v_mov_b32_dpp v177, v86 row_ror:1 row_mask:0xf bank_mask:0xf bound_ctrl:1
	v_cndmask_b32_e64 v138, v180, v178, s[12:13]
	v_mov_b32_dpp v180, v87 row_ror:2 row_mask:0xf bank_mask:0xf bound_ctrl:1
	v_cndmask_b32_e64 v136, v177, v179, s[10:11]
	v_mov_b32_dpp v179, v87 row_ror:1 row_mask:0xf bank_mask:0xf bound_ctrl:1
	v_cndmask_b32_e64 v139, v115, v180, s[12:13]
	v_cndmask_b32_e64 v137, v179, v0, s[10:11]
	v_pk_fma_f32 v[138:139], v[198:199], v[138:139], v[202:203]
	v_mov_b32_dpp v115, v88 row_ror:2 row_mask:0xf bank_mask:0xf bound_ctrl:1
	v_pk_fma_f32 v[136:137], v[206:207], v[136:137], v[138:139]
	v_mov_b32_dpp v0, v88 row_ror:1 row_mask:0xf bank_mask:0xf bound_ctrl:1
	v_pk_fma_f32 v[136:137], v[86:87], v[232:233], v[136:137]
	v_cndmask_b32_e64 v142, v145, v115, s[12:13]
	v_mov_b32_dpp v145, v89 row_ror:2 row_mask:0xf bank_mask:0xf bound_ctrl:1
	v_mul_f32_e32 v86, 0xbfb8aa3b, v136
	v_cndmask_b32_e64 v140, v0, v144, s[10:11]
	v_mov_b32_dpp v144, v89 row_ror:1 row_mask:0xf bank_mask:0xf bound_ctrl:1
	v_cndmask_b32_e64 v143, v176, v145, s[12:13]
	v_exp_f32_e32 v138, v86
	v_cndmask_b32_e64 v141, v144, v159, s[10:11]
	v_pk_fma_f32 v[86:87], v[200:201], v[142:143], v[204:205]
	s_nop 0
	v_pk_fma_f32 v[86:87], v[208:209], v[140:141], v[86:87]
	s_nop 0
	v_pk_fma_f32 v[86:87], v[88:89], v[234:235], v[86:87]
	v_add_f32_e32 v88, 1.0, v138
	v_mul_f32_e32 v89, 0xbfb8aa3b, v137
	v_mul_f32_e32 v138, 0xbfb8aa3b, v86
	v_mul_f32_e32 v139, 0xbfb8aa3b, v87
	v_exp_f32_e32 v89, v89
	v_exp_f32_e32 v138, v138
	v_exp_f32_e32 v139, v139
	v_rcp_f32_e32 v88, v88
	v_add_f32_e32 v89, 1.0, v89
	v_add_f32_e32 v138, 1.0, v138
	v_add_f32_e32 v139, 1.0, v139
	v_rcp_f32_e32 v138, v138
	v_rcp_f32_e32 v139, v139
	v_rcp_f32_e32 v89, v89
	v_pk_mul_f32 v[86:87], v[86:87], v[138:139]
	v_pk_mul_f32 v[88:89], v[136:137], v[88:89]
	v_mov_b32_dpp v137, v82 row_ror:2 row_mask:0xf bank_mask:0xf bound_ctrl:1
	v_mov_b32_dpp v139, v83 row_ror:2 row_mask:0xf bank_mask:0xf bound_ctrl:1
	v_mov_b32_dpp v136, v82 row_ror:1 row_mask:0xf bank_mask:0xf bound_ctrl:1
	v_cndmask_b32_e64 v138, v178, v137, s[12:13]
	v_mov_b32_dpp v137, v83 row_ror:1 row_mask:0xf bank_mask:0xf bound_ctrl:1
	v_cndmask_b32_e64 v139, v180, v139, s[12:13]
	v_cndmask_b32_e64 v136, v136, v177, s[10:11]
	v_cndmask_b32_e64 v137, v137, v179, s[10:11]
	v_pk_fma_f32 v[138:139], v[198:199], v[138:139], v[202:203]
	v_mov_b32_dpp v140, v84 row_ror:1 row_mask:0xf bank_mask:0xf bound_ctrl:1
	v_pk_fma_f32 v[136:137], v[206:207], v[136:137], v[138:139]
	v_mov_b32_dpp v141, v84 row_ror:2 row_mask:0xf bank_mask:0xf bound_ctrl:1
	v_cndmask_b32_e64 v140, v140, v0, s[10:11]
	v_mov_b32_dpp v0, v85 row_ror:1 row_mask:0xf bank_mask:0xf bound_ctrl:1
	v_pk_fma_f32 v[136:137], v[82:83], v[232:233], v[136:137]
	v_cndmask_b32_e64 v142, v115, v141, s[12:13]
	v_mov_b32_dpp v115, v85 row_ror:2 row_mask:0xf bank_mask:0xf bound_ctrl:1
	v_cndmask_b32_e64 v141, v0, v144, s[10:11]
	v_mul_f32_e32 v0, 0xbfb8aa3b, v136
	v_cndmask_b32_e64 v143, v145, v115, s[12:13]
; __device__ __forceinline__ f32x4 sigm4(f32x4 v) { f32x4 o; o[0] = sigm(v[0]); o[1] = sigm(v[1]); o[2] = sigm(v[2]); o[3] = sigm(v[3]); return o; }
; __device__ __forceinline__ float dppr1(float x) { return __int_as_float(__builtin_amdgcn_mov_dpp(__float_as_int(x), 0x121, 0xf, 0xf, true)); }
; __device__ __forceinline__ float dppr2(float x) { return __int_as_float(__builtin_amdgcn_mov_dpp(__float_as_int(x), 0x122, 0xf, 0xf, true)); }
;     template <int GV, int NH> __device__ __forceinline__ void part(f32x4 (&acc)[2][2][4][2], const Unit& u, int wr, int wc, int fr, int fq) const {
;     ...
;             for (int m = 0; m < 4; ++m) {
;                 const f32x4 x3 = acc[ai][GV][m][NH];
;                 f32x4 c1, c2, x2, x1;
; #pragma unroll
;                 for (int i = 0; i < 4; ++i) { c1[i] = dppr1(x3[i]); c2[i] = dppr2(x3[i]); x2[i] = f1 ? c1[i] : p1[i]; x1[i] = f2 ? c2[i] : p2[i]; }
;                 p1 = c1; p2 = c2;
;                 const f32x4 o = bb + x1 * w0 + x2 * w1 + x3 * w2;
;                 if (GV == 0) acc[ai][0][m][NH] = o * sigm4(o);
	v_exp_f32_e32 v0, v0
	v_pk_fma_f32 v[82:83], v[200:201], v[142:143], v[204:205]
	v_add_f32_e32 v0, 1.0, v0
	v_pk_fma_f32 v[82:83], v[208:209], v[140:141], v[82:83]
	s_nop 0
	v_pk_fma_f32 v[82:83], v[84:85], v[234:235], v[82:83]
	v_rcp_f32_e32 v84, v0
	v_mul_f32_e32 v85, 0xbfb8aa3b, v82
	v_mul_f32_e32 v0, 0xbfb8aa3b, v137
	v_exp_f32_e32 v85, v85
	v_mul_f32_e32 v115, 0xbfb8aa3b, v83
	v_exp_f32_e32 v0, v0
	v_exp_f32_e32 v115, v115
	v_add_f32_e32 v85, 1.0, v85
	v_rcp_f32_e32 v138, v85
	v_add_f32_e32 v0, 1.0, v0
	v_add_f32_e32 v85, 1.0, v115
	v_rcp_f32_e32 v139, v85
	v_rcp_f32_e32 v85, v0
	v_pk_mul_f32 v[82:83], v[82:83], v[138:139]
	v_pk_mul_f32 v[84:85], v[136:137], v[84:85]
	v_mov_b32_dpp v115, v78 row_ror:2 row_mask:0xf bank_mask:0xf bound_ctrl:1
	v_mov_b32_dpp v145, v79 row_ror:2 row_mask:0xf bank_mask:0xf bound_ctrl:1
	v_mov_b32_dpp v176, v80 row_ror:2 row_mask:0xf bank_mask:0xf bound_ctrl:1
	v_mov_b32_dpp v178, v81 row_ror:2 row_mask:0xf bank_mask:0xf bound_ctrl:1
	v_mov_b32_dpp v0, v78 row_ror:1 row_mask:0xf bank_mask:0xf bound_ctrl:1
	v_cndmask_b32_e64 v138, 0, v115, s[12:13]
	v_mov_b32_dpp v144, v79 row_ror:1 row_mask:0xf bank_mask:0xf bound_ctrl:1
	v_cndmask_b32_e64 v139, 0, v145, s[12:13]
	v_mov_b32_dpp v159, v80 row_ror:1 row_mask:0xf bank_mask:0xf bound_ctrl:1
	v_cndmask_b32_e64 v142, 0, v176, s[12:13]
	v_mov_b32_dpp v177, v81 row_ror:1 row_mask:0xf bank_mask:0xf bound_ctrl:1
	v_cndmask_b32_e64 v143, 0, v178, s[12:13]
	v_cndmask_b32_e64 v136, v0, 0, s[10:11]
	v_cndmask_b32_e64 v137, v144, 0, s[10:11]
	v_cndmask_b32_e64 v140, v159, 0, s[10:11]
	v_cndmask_b32_e64 v141, v177, 0, s[10:11]
	v_pk_fma_f32 v[142:143], v[200:201], v[142:143], v[204:205]
	v_pk_fma_f32 v[138:139], v[198:199], v[138:139], v[202:203]
	s_nop 0
	v_pk_fma_f32 v[136:137], v[206:207], v[136:137], v[138:139]
	v_pk_fma_f32 v[138:139], v[208:209], v[140:141], v[142:143]
	v_pk_fma_f32 v[78:79], v[78:79], v[232:233], v[136:137]
	v_pk_fma_f32 v[80:81], v[80:81], v[234:235], v[138:139]
	v_mul_f32_e32 v136, 0xbfb8aa3b, v78
	v_mul_f32_e32 v137, 0xbfb8aa3b, v79
	v_mul_f32_e32 v138, 0xbfb8aa3b, v80
	v_mul_f32_e32 v139, 0xbfb8aa3b, v81
	v_exp_f32_e32 v136, v136
	v_exp_f32_e32 v137, v137
	v_exp_f32_e32 v138, v138
	v_exp_f32_e32 v139, v139
	v_add_f32_e32 v136, 1.0, v136
	v_add_f32_e32 v137, 1.0, v137
	v_add_f32_e32 v138, 1.0, v138
	v_add_f32_e32 v139, 1.0, v139
	v_rcp_f32_e32 v136, v136
	v_rcp_f32_e32 v137, v137
	v_rcp_f32_e32 v138, v138
	v_rcp_f32_e32 v139, v139
	v_pk_mul_f32 v[136:137], v[78:79], v[136:137]
	v_pk_mul_f32 v[138:139], v[80:81], v[138:139]
	v_mov_b32_dpp v180, v74 row_ror:2 row_mask:0xf bank_mask:0xf bound_ctrl:1
	v_mov_b32_dpp v179, v74 row_ror:1 row_mask:0xf bank_mask:0xf bound_ctrl:1
	v_cndmask_b32_e64 v80, v115, v180, s[12:13]
	v_mov_b32_dpp v115, v75 row_ror:2 row_mask:0xf bank_mask:0xf bound_ctrl:1
	v_cndmask_b32_e64 v78, v179, v0, s[10:11]
	v_mov_b32_dpp v0, v75 row_ror:1 row_mask:0xf bank_mask:0xf bound_ctrl:1
	v_cndmask_b32_e64 v81, v145, v115, s[12:13]
	v_cndmask_b32_e64 v79, v0, v144, s[10:11]
	v_pk_fma_f32 v[80:81], v[198:199], v[80:81], v[202:203]
	v_mov_b32_dpp v145, v76 row_ror:2 row_mask:0xf bank_mask:0xf bound_ctrl:1
	v_pk_fma_f32 v[78:79], v[206:207], v[78:79], v[80:81]
	v_mov_b32_dpp v144, v76 row_ror:1 row_mask:0xf bank_mask:0xf bound_ctrl:1
	v_pk_fma_f32 v[74:75], v[74:75], v[232:233], v[78:79]
	v_cndmask_b32_e64 v142, v176, v145, s[12:13]
	v_mov_b32_dpp v176, v77 row_ror:2 row_mask:0xf bank_mask:0xf bound_ctrl:1
	v_mul_f32_e32 v78, 0xbfb8aa3b, v74
	v_cndmask_b32_e64 v140, v144, v159, s[10:11]
	v_mov_b32_dpp v159, v77 row_ror:1 row_mask:0xf bank_mask:0xf bound_ctrl:1
	v_cndmask_b32_e64 v143, v178, v176, s[12:13]
	v_exp_f32_e32 v80, v78
	v_cndmask_b32_e64 v141, v159, v177, s[10:11]
	v_pk_fma_f32 v[78:79], v[200:201], v[142:143], v[204:205]
	s_nop 0
	v_pk_fma_f32 v[78:79], v[208:209], v[140:141], v[78:79]
	s_nop 0
	v_pk_fma_f32 v[76:77], v[76:77], v[234:235], v[78:79]
	v_add_f32_e32 v78, 1.0, v80
	v_mul_f32_e32 v79, 0xbfb8aa3b, v75
	v_mul_f32_e32 v80, 0xbfb8aa3b, v76
	v_mul_f32_e32 v81, 0xbfb8aa3b, v77
	v_exp_f32_e32 v79, v79
	v_exp_f32_e32 v80, v80
	v_exp_f32_e32 v81, v81
	v_rcp_f32_e32 v78, v78
	v_add_f32_e32 v79, 1.0, v79
	v_add_f32_e32 v80, 1.0, v80
	v_add_f32_e32 v81, 1.0, v81
	v_rcp_f32_e32 v80, v80
	v_rcp_f32_e32 v81, v81
	v_rcp_f32_e32 v79, v79
	v_pk_mul_f32 v[140:141], v[76:77], v[80:81]
	v_pk_mul_f32 v[142:143], v[74:75], v[78:79]
	v_mov_b32_dpp v181, v70 row_ror:2 row_mask:0xf bank_mask:0xf bound_ctrl:1
	v_mov_b32_dpp v178, v70 row_ror:1 row_mask:0xf bank_mask:0xf bound_ctrl:1
	v_cndmask_b32_e64 v76, v180, v181, s[12:13]
	v_mov_b32_dpp v180, v71 row_ror:2 row_mask:0xf bank_mask:0xf bound_ctrl:1
	v_cndmask_b32_e64 v74, v178, v179, s[10:11]
	v_mov_b32_dpp v179, v71 row_ror:1 row_mask:0xf bank_mask:0xf bound_ctrl:1
	v_cndmask_b32_e64 v77, v115, v180, s[12:13]
	v_cndmask_b32_e64 v75, v179, v0, s[10:11]
	v_pk_fma_f32 v[76:77], v[198:199], v[76:77], v[202:203]
	v_mov_b32_dpp v115, v72 row_ror:2 row_mask:0xf bank_mask:0xf bound_ctrl:1
	v_pk_fma_f32 v[74:75], v[206:207], v[74:75], v[76:77]
	v_mov_b32_dpp v187, v73 row_ror:2 row_mask:0xf bank_mask:0xf bound_ctrl:1
	v_pk_fma_f32 v[70:71], v[70:71], v[232:233], v[74:75]
	v_mov_b32_dpp v0, v72 row_ror:1 row_mask:0xf bank_mask:0xf bound_ctrl:1
	v_mul_f32_e32 v74, 0xbfb8aa3b, v70
	v_cndmask_b32_e64 v80, v145, v115, s[12:13]
	v_mov_b32_dpp v186, v73 row_ror:1 row_mask:0xf bank_mask:0xf bound_ctrl:1
	v_cndmask_b32_e64 v81, v176, v187, s[12:13]
	v_exp_f32_e32 v76, v74
	v_cndmask_b32_e64 v78, v0, v144, s[10:11]
	v_cndmask_b32_e64 v79, v186, v159, s[10:11]
	v_pk_fma_f32 v[74:75], v[200:201], v[80:81], v[204:205]
; __device__ __forceinline__ unsigned cvt_pk(float lo, float hi) { f32x2_t v = {lo, hi}; bf16x2_t b = __builtin_convertvector(v, bf16x2_t); return __builtin_bit_cast(unsigned, b); }
; __device__ __forceinline__ f32x4 sigm4(f32x4 v) { f32x4 o; o[0] = sigm(v[0]); o[1] = sigm(v[1]); o[2] = sigm(v[2]); o[3] = sigm(v[3]); return o; }
; __device__ __forceinline__ float dppr1(float x) { return __int_as_float(__builtin_amdgcn_mov_dpp(__float_as_int(x), 0x121, 0xf, 0xf, true)); }
; __device__ __forceinline__ float dppr2(float x) { return __int_as_float(__builtin_amdgcn_mov_dpp(__float_as_int(x), 0x122, 0xf, 0xf, true)); }
;     template <int GV, int NH> __device__ __forceinline__ void part(f32x4 (&acc)[2][2][4][2], const Unit& u, int wr, int wc, int fr, int fq) const {
;     ...
;         const f32x4 w0 = *(const f32x4*)(cw + GV * DFF + jg), w1 = *(const f32x4*)(cw + NUP + GV * DFF + jg), w2 = *(const f32x4*)(cw + 2 * NUP + GV * DFF + jg), bb = *(const f32x4*)(cb + GV * DFF + jg);
;     ...
;             for (int m = 0; m < 4; ++m) {
;                 const f32x4 x3 = acc[ai][GV][m][NH];
;                 f32x4 c1, c2, x2, x1;
; #pragma unroll
;                 for (int i = 0; i < 4; ++i) { c1[i] = dppr1(x3[i]); c2[i] = dppr2(x3[i]); x2[i] = f1 ? c1[i] : p1[i]; x1[i] = f2 ? c2[i] : p2[i]; }
;                 p1 = c1; p2 = c2;
;                 const f32x4 o = bb + x1 * w0 + x2 * w1 + x3 * w2;
;                 if (GV == 0) acc[ai][0][m][NH] = o * sigm4(o);
;                 else { const f32x4 r = acc[ai][0][m][NH] * o; u32x2 pk; pk.x = cvt_pk(r[0], r[1]); pk.y = cvt_pk(r[2], r[3]); *(u32x2*)(ACT + rowb + (unsigned)(16 * m) * DFF) = pk; }
	s_nop 0
	v_pk_fma_f32 v[74:75], v[208:209], v[78:79], v[74:75]
	s_nop 0
	v_pk_fma_f32 v[72:73], v[72:73], v[234:235], v[74:75]
	v_add_f32_e32 v74, 1.0, v76
	v_mul_f32_e32 v75, 0xbfb8aa3b, v71
	v_mul_f32_e32 v76, 0xbfb8aa3b, v72
	v_mul_f32_e32 v77, 0xbfb8aa3b, v73
	v_exp_f32_e32 v75, v75
	v_exp_f32_e32 v76, v76
	v_exp_f32_e32 v77, v77
	v_rcp_f32_e32 v74, v74
	v_add_f32_e32 v75, 1.0, v75
	v_add_f32_e32 v76, 1.0, v76
	v_add_f32_e32 v77, 1.0, v77
	v_rcp_f32_e32 v76, v76
	v_rcp_f32_e32 v77, v77
	v_rcp_f32_e32 v75, v75
	v_pk_mul_f32 v[144:145], v[72:73], v[76:77]
	v_pk_mul_f32 v[176:177], v[70:71], v[74:75]
	v_mov_b32_dpp v71, v66 row_ror:2 row_mask:0xf bank_mask:0xf bound_ctrl:1
	v_mov_b32_dpp v73, v67 row_ror:2 row_mask:0xf bank_mask:0xf bound_ctrl:1
	v_mov_b32_dpp v70, v66 row_ror:1 row_mask:0xf bank_mask:0xf bound_ctrl:1
	v_cndmask_b32_e64 v72, v181, v71, s[12:13]
	v_mov_b32_dpp v71, v67 row_ror:1 row_mask:0xf bank_mask:0xf bound_ctrl:1
	v_cndmask_b32_e64 v73, v180, v73, s[12:13]
	v_cndmask_b32_e64 v70, v70, v178, s[10:11]
	v_cndmask_b32_e64 v71, v71, v179, s[10:11]
	v_pk_fma_f32 v[72:73], v[198:199], v[72:73], v[202:203]
	v_mov_b32_dpp v74, v68 row_ror:1 row_mask:0xf bank_mask:0xf bound_ctrl:1
	v_pk_fma_f32 v[70:71], v[206:207], v[70:71], v[72:73]
	v_mov_b32_dpp v75, v68 row_ror:2 row_mask:0xf bank_mask:0xf bound_ctrl:1
	v_cndmask_b32_e64 v74, v74, v0, s[10:11]
	v_mov_b32_dpp v0, v69 row_ror:1 row_mask:0xf bank_mask:0xf bound_ctrl:1
	v_pk_fma_f32 v[66:67], v[66:67], v[232:233], v[70:71]
	v_cndmask_b32_e64 v76, v115, v75, s[12:13]
	v_mov_b32_dpp v77, v69 row_ror:2 row_mask:0xf bank_mask:0xf bound_ctrl:1
	v_cndmask_b32_e64 v75, v0, v186, s[10:11]
	v_mul_f32_e32 v0, 0xbfb8aa3b, v66
	v_cndmask_b32_e64 v77, v187, v77, s[12:13]
	v_exp_f32_e32 v0, v0
	v_pk_fma_f32 v[70:71], v[200:201], v[76:77], v[204:205]
	v_add_f32_e32 v0, 1.0, v0
	v_pk_fma_f32 v[70:71], v[208:209], v[74:75], v[70:71]
	s_nop 0
	v_pk_fma_f32 v[68:69], v[68:69], v[234:235], v[70:71]
	v_rcp_f32_e32 v70, v0
	v_mul_f32_e32 v71, 0xbfb8aa3b, v68
	v_mul_f32_e32 v0, 0xbfb8aa3b, v67
	v_exp_f32_e32 v71, v71
	v_mul_f32_e32 v72, 0xbfb8aa3b, v69
	v_exp_f32_e32 v0, v0
	v_exp_f32_e32 v73, v72
	v_add_f32_e32 v71, 1.0, v71
	v_rcp_f32_e32 v72, v71
	v_add_f32_e32 v0, 1.0, v0
	v_add_f32_e32 v71, 1.0, v73
	v_rcp_f32_e32 v73, v71
	v_rcp_f32_e32 v71, v0
	v_pk_mul_f32 v[98:99], v[68:69], v[72:73]
	v_pk_mul_f32 v[100:101], v[66:67], v[70:71]
	v_lshl_add_u64 v[66:67], s[56:57], 0, v[160:161]
	v_lshl_add_u64 v[70:71], s[76:77], 0, v[160:161]
	global_load_dwordx4 v[66:69], v[66:67], off
	v_mov_b32_dpp v111, v62 row_ror:2 row_mask:0xf bank_mask:0xf bound_ctrl:1
	global_load_dwordx4 v[78:81], v[70:71], off
	v_lshl_add_u64 v[70:71], s[58:59], 0, v[160:161]
	global_load_dwordx4 v[74:77], v[70:71], off
	v_lshl_add_u64 v[70:71], s[66:67], 0, v[160:161]
	global_load_dwordx4 v[70:73], v[70:71], off
	v_lshl_add_u64 v[220:221], s[56:57], 0, v[160:161]
	global_load_dwordx4 v[238:241], v[220:221], off offset:16
	v_lshl_add_u64 v[220:221], s[76:77], 0, v[160:161]
	global_load_dwordx4 v[242:245], v[220:221], off offset:16
	v_lshl_add_u64 v[220:221], s[58:59], 0, v[160:161]
	global_load_dwordx4 v[198:201], v[220:221], off offset:16
	v_lshl_add_u64 v[220:221], s[66:67], 0, v[160:161]
	global_load_dwordx4 v[202:205], v[220:221], off offset:16
	v_mov_b32_dpp v113, v63 row_ror:2 row_mask:0xf bank_mask:0xf bound_ctrl:1
	v_mov_b32_dpp v159, v64 row_ror:2 row_mask:0xf bank_mask:0xf bound_ctrl:1
	v_mov_b32_dpp v161, v65 row_ror:2 row_mask:0xf bank_mask:0xf bound_ctrl:1
	v_mov_b32_dpp v110, v62 row_ror:1 row_mask:0xf bank_mask:0xf bound_ctrl:1
	v_mov_b32_dpp v112, v63 row_ror:1 row_mask:0xf bank_mask:0xf bound_ctrl:1
	v_mov_b32_dpp v115, v64 row_ror:1 row_mask:0xf bank_mask:0xf bound_ctrl:1
	v_mov_b32_dpp v160, v65 row_ror:1 row_mask:0xf bank_mask:0xf bound_ctrl:1
	v_cndmask_b32_e64 v104, 0, v111, s[12:13]
	v_cndmask_b32_e64 v105, 0, v113, s[12:13]
	v_cndmask_b32_e64 v108, 0, v159, s[12:13]
	v_cndmask_b32_e64 v109, 0, v161, s[12:13]
	v_cndmask_b32_e64 v102, v110, 0, s[10:11]
	v_cndmask_b32_e64 v103, v112, 0, s[10:11]
	v_cndmask_b32_e64 v106, v115, 0, s[10:11]
	v_cndmask_b32_e64 v107, v160, 0, s[10:11]
	v_add_u32_e32 v0, s25, v188
	s_movk_i32 s16, 0xb00
	v_mul_lo_u32 v178, v0, s16
	v_add_u32_e32 v0, v178, v158
	s_waitcnt vmcnt(6)
	v_pk_fma_f32 v[108:109], v[68:69], v[108:109], v[80:81]
	v_pk_fma_f32 v[104:105], v[66:67], v[104:105], v[78:79]
	s_waitcnt vmcnt(5)
	v_pk_fma_f32 v[106:107], v[76:77], v[106:107], v[108:109]
	v_pk_fma_f32 v[102:103], v[74:75], v[102:103], v[104:105]
	s_waitcnt vmcnt(4)
; __device__ __forceinline__ unsigned cvt_pk(float lo, float hi) { f32x2_t v = {lo, hi}; bf16x2_t b = __builtin_convertvector(v, bf16x2_t); return __builtin_bit_cast(unsigned, b); }
; __device__ __forceinline__ f32x4 sigm4(f32x4 v) { f32x4 o; o[0] = sigm(v[0]); o[1] = sigm(v[1]); o[2] = sigm(v[2]); o[3] = sigm(v[3]); return o; }
; __device__ __forceinline__ float dppr1(float x) { return __int_as_float(__builtin_amdgcn_mov_dpp(__float_as_int(x), 0x121, 0xf, 0xf, true)); }
; __device__ __forceinline__ float dppr2(float x) { return __int_as_float(__builtin_amdgcn_mov_dpp(__float_as_int(x), 0x122, 0xf, 0xf, true)); }
;     template <int GV, int NH> __device__ __forceinline__ void part(f32x4 (&acc)[2][2][4][2], const Unit& u, int wr, int wc, int fr, int fq) const {
;     ...
;             for (int m = 0; m < 4; ++m) {
;                 const f32x4 x3 = acc[ai][GV][m][NH];
;                 f32x4 c1, c2, x2, x1;
; #pragma unroll
;                 for (int i = 0; i < 4; ++i) { c1[i] = dppr1(x3[i]); c2[i] = dppr2(x3[i]); x2[i] = f1 ? c1[i] : p1[i]; x1[i] = f2 ? c2[i] : p2[i]; }
;                 p1 = c1; p2 = c2;
;                 const f32x4 o = bb + x1 * w0 + x2 * w1 + x3 * w2;
;                 if (GV == 0) acc[ai][0][m][NH] = o * sigm4(o);
;                 else { const f32x4 r = acc[ai][0][m][NH] * o; u32x2 pk; pk.x = cvt_pk(r[0], r[1]); pk.y = cvt_pk(r[2], r[3]); *(u32x2*)(ACT + rowb + (unsigned)(16 * m) * DFF) = pk; }
	v_pk_fma_f32 v[64:65], v[64:65], v[72:73], v[106:107]
	v_pk_fma_f32 v[62:63], v[62:63], v[70:71], v[102:103]
	v_pk_mul_f32 v[64:65], v[126:127], v[64:65]
	v_pk_mul_f32 v[62:63], v[128:129], v[62:63]
	s_nop 0
	v_cvt_pk_bf16_f32 v62, v62, v63
	v_cvt_pk_bf16_f32 v63, v64, v65
	v_lshl_add_u64 v[64:65], v[0:1], 1, s[36:37]
	global_store_dwordx2 v[64:65], v[62:63], off
	v_mov_b32_dpp v108, v58 row_ror:2 row_mask:0xf bank_mask:0xf bound_ctrl:1
	v_mov_b32_dpp v0, v58 row_ror:1 row_mask:0xf bank_mask:0xf bound_ctrl:1
	v_cndmask_b32_e64 v102, v111, v108, s[12:13]
	v_mov_b32_dpp v109, v59 row_ror:1 row_mask:0xf bank_mask:0xf bound_ctrl:1
	v_mov_b32_dpp v111, v60 row_ror:1 row_mask:0xf bank_mask:0xf bound_ctrl:1
	v_cndmask_b32_e64 v62, v0, v110, s[10:11]
	v_mov_b32_dpp v110, v59 row_ror:2 row_mask:0xf bank_mask:0xf bound_ctrl:1
	v_cndmask_b32_e64 v63, v109, v112, s[10:11]
	v_mov_b32_dpp v112, v60 row_ror:2 row_mask:0xf bank_mask:0xf bound_ctrl:1
	v_cndmask_b32_e64 v104, v111, v115, s[10:11]
	v_mov_b32_dpp v115, v61 row_ror:2 row_mask:0xf bank_mask:0xf bound_ctrl:1
	v_cndmask_b32_e64 v103, v113, v110, s[12:13]
	v_cndmask_b32_e64 v106, v159, v112, s[12:13]
	v_mov_b32_dpp v113, v61 row_ror:1 row_mask:0xf bank_mask:0xf bound_ctrl:1
	v_cndmask_b32_e64 v107, v161, v115, s[12:13]
	v_cndmask_b32_e64 v105, v113, v160, s[10:11]
	v_pk_fma_f32 v[102:103], v[66:67], v[102:103], v[78:79]
	v_pk_fma_f32 v[106:107], v[68:69], v[106:107], v[80:81]
	v_pk_fma_f32 v[62:63], v[74:75], v[62:63], v[102:103]
	v_pk_fma_f32 v[104:105], v[76:77], v[104:105], v[106:107]
	v_pk_fma_f32 v[58:59], v[58:59], v[70:71], v[62:63]
	v_pk_fma_f32 v[60:61], v[60:61], v[72:73], v[104:105]
	v_pk_mul_f32 v[58:59], v[122:123], v[58:59]
	v_pk_mul_f32 v[60:61], v[124:125], v[60:61]
	s_mov_b32 s0, 0x16000
	v_cvt_pk_bf16_f32 v58, v58, v59
	v_cvt_pk_bf16_f32 v59, v60, v61
	v_add_co_u32_e32 v60, vcc, s0, v64
	s_nop 1
	v_addc_co_u32_e32 v61, vcc, 0, v65, vcc
	global_store_dwordx2 v[60:61], v[58:59], off
	v_mov_b32_dpp v104, v54 row_ror:1 row_mask:0xf bank_mask:0xf bound_ctrl:1
	v_mov_b32_dpp v105, v54 row_ror:2 row_mask:0xf bank_mask:0xf bound_ctrl:1
	v_mov_b32_dpp v106, v55 row_ror:2 row_mask:0xf bank_mask:0xf bound_ctrl:1
	v_cndmask_b32_e64 v58, v104, v0, s[10:11]
	v_cndmask_b32_e64 v60, v108, v105, s[12:13]
	v_mov_b32_dpp v0, v55 row_ror:1 row_mask:0xf bank_mask:0xf bound_ctrl:1
	v_cndmask_b32_e64 v61, v110, v106, s[12:13]
	v_mov_b32_dpp v108, v56 row_ror:2 row_mask:0xf bank_mask:0xf bound_ctrl:1
	v_mov_b32_dpp v110, v57 row_ror:2 row_mask:0xf bank_mask:0xf bound_ctrl:1
	v_cndmask_b32_e64 v59, v0, v109, s[10:11]
	v_mov_b32_dpp v107, v56 row_ror:1 row_mask:0xf bank_mask:0xf bound_ctrl:1
	v_cndmask_b32_e64 v102, v112, v108, s[12:13]
	v_mov_b32_dpp v109, v57 row_ror:1 row_mask:0xf bank_mask:0xf bound_ctrl:1
	v_cndmask_b32_e64 v103, v115, v110, s[12:13]
	v_cndmask_b32_e64 v62, v107, v111, s[10:11]
	v_cndmask_b32_e64 v63, v109, v113, s[10:11]
	v_pk_fma_f32 v[60:61], v[66:67], v[60:61], v[78:79]
	v_pk_fma_f32 v[102:103], v[68:69], v[102:103], v[80:81]
	v_pk_fma_f32 v[58:59], v[74:75], v[58:59], v[60:61]
	v_pk_fma_f32 v[62:63], v[76:77], v[62:63], v[102:103]
	v_pk_fma_f32 v[54:55], v[54:55], v[70:71], v[58:59]
	v_pk_fma_f32 v[56:57], v[56:57], v[72:73], v[62:63]
	v_pk_mul_f32 v[54:55], v[118:119], v[54:55]
	v_pk_mul_f32 v[56:57], v[120:121], v[56:57]
	s_mov_b32 s17, 0x2c000
	v_cvt_pk_bf16_f32 v54, v54, v55
	v_cvt_pk_bf16_f32 v55, v56, v57
	v_add_co_u32_e32 v56, vcc, s17, v64
	s_nop 1
	v_addc_co_u32_e32 v57, vcc, 0, v65, vcc
	global_store_dwordx2 v[56:57], v[54:55], off
	v_mov_b32_dpp v55, v50 row_ror:2 row_mask:0xf bank_mask:0xf bound_ctrl:1
	v_cndmask_b32_e64 v56, v105, v55, s[12:13]
	v_mov_b32_dpp v57, v51 row_ror:2 row_mask:0xf bank_mask:0xf bound_ctrl:1
	v_mov_b32_dpp v55, v51 row_ror:1 row_mask:0xf bank_mask:0xf bound_ctrl:1
	v_cndmask_b32_e64 v55, v55, v0, s[10:11]
	v_mov_b32_dpp v0, v52 row_ror:1 row_mask:0xf bank_mask:0xf bound_ctrl:1
	v_mov_b32_dpp v59, v52 row_ror:2 row_mask:0xf bank_mask:0xf bound_ctrl:1
	v_mov_b32_dpp v61, v53 row_ror:2 row_mask:0xf bank_mask:0xf bound_ctrl:1
	v_mov_b32_dpp v54, v50 row_ror:1 row_mask:0xf bank_mask:0xf bound_ctrl:1
	v_cndmask_b32_e64 v57, v106, v57, s[12:13]
	v_cndmask_b32_e64 v58, v0, v107, s[10:11]
	v_cndmask_b32_e64 v60, v108, v59, s[12:13]
	v_mov_b32_dpp v0, v53 row_ror:1 row_mask:0xf bank_mask:0xf bound_ctrl:1
	v_cndmask_b32_e64 v61, v110, v61, s[12:13]
	v_cndmask_b32_e64 v54, v54, v104, s[10:11]
	v_cndmask_b32_e64 v59, v0, v109, s[10:11]
	v_pk_fma_f32 v[56:57], v[66:67], v[56:57], v[78:79]
	v_pk_fma_f32 v[60:61], v[68:69], v[60:61], v[80:81]
	v_pk_fma_f32 v[54:55], v[74:75], v[54:55], v[56:57]
	v_pk_fma_f32 v[58:59], v[76:77], v[58:59], v[60:61]
	v_pk_fma_f32 v[50:51], v[50:51], v[70:71], v[54:55]
	v_pk_fma_f32 v[52:53], v[52:53], v[72:73], v[58:59]
	v_pk_mul_f32 v[50:51], v[116:117], v[50:51]
	v_pk_mul_f32 v[52:53], v[162:163], v[52:53]
	s_mov_b32 s1, 0x42000
	v_cvt_pk_bf16_f32 v50, v50, v51
	v_cvt_pk_bf16_f32 v51, v52, v53
	v_add_co_u32_e32 v52, vcc, s1, v64
	s_nop 1
	v_addc_co_u32_e32 v53, vcc, 0, v65, vcc
	global_store_dwordx2 v[52:53], v[50:51], off
	v_mov_b32_dpp v60, v46 row_ror:2 row_mask:0xf bank_mask:0xf bound_ctrl:1
	v_mov_b32_dpp v62, v47 row_ror:2 row_mask:0xf bank_mask:0xf bound_ctrl:1
	v_mov_b32_dpp v64, v48 row_ror:2 row_mask:0xf bank_mask:0xf bound_ctrl:1
	v_mov_b32_dpp v102, v49 row_ror:2 row_mask:0xf bank_mask:0xf bound_ctrl:1
	v_mov_b32_dpp v59, v46 row_ror:1 row_mask:0xf bank_mask:0xf bound_ctrl:1
	v_cndmask_b32_e64 v52, 0, v60, s[12:13]
	v_mov_b32_dpp v61, v47 row_ror:1 row_mask:0xf bank_mask:0xf bound_ctrl:1
; __device__ __forceinline__ unsigned cvt_pk(float lo, float hi) { f32x2_t v = {lo, hi}; bf16x2_t b = __builtin_convertvector(v, bf16x2_t); return __builtin_bit_cast(unsigned, b); }
; __device__ __forceinline__ f32x4 sigm4(f32x4 v) { f32x4 o; o[0] = sigm(v[0]); o[1] = sigm(v[1]); o[2] = sigm(v[2]); o[3] = sigm(v[3]); return o; }
; __device__ __forceinline__ float dppr1(float x) { return __int_as_float(__builtin_amdgcn_mov_dpp(__float_as_int(x), 0x121, 0xf, 0xf, true)); }
; __device__ __forceinline__ float dppr2(float x) { return __int_as_float(__builtin_amdgcn_mov_dpp(__float_as_int(x), 0x122, 0xf, 0xf, true)); }
;     template <int GV, int NH> __device__ __forceinline__ void part(f32x4 (&acc)[2][2][4][2], const Unit& u, int wr, int wc, int fr, int fq) const {
;     ...
;             for (int m = 0; m < 4; ++m) {
;                 const f32x4 x3 = acc[ai][GV][m][NH];
;                 f32x4 c1, c2, x2, x1;
; #pragma unroll
;                 for (int i = 0; i < 4; ++i) { c1[i] = dppr1(x3[i]); c2[i] = dppr2(x3[i]); x2[i] = f1 ? c1[i] : p1[i]; x1[i] = f2 ? c2[i] : p2[i]; }
;                 p1 = c1; p2 = c2;
;                 const f32x4 o = bb + x1 * w0 + x2 * w1 + x3 * w2;
;                 if (GV == 0) acc[ai][0][m][NH] = o * sigm4(o);
;                 else { const f32x4 r = acc[ai][0][m][NH] * o; u32x2 pk; pk.x = cvt_pk(r[0], r[1]); pk.y = cvt_pk(r[2], r[3]); *(u32x2*)(ACT + rowb + (unsigned)(16 * m) * DFF) = pk; }
	v_cndmask_b32_e64 v53, 0, v62, s[12:13]
	v_mov_b32_dpp v63, v48 row_ror:1 row_mask:0xf bank_mask:0xf bound_ctrl:1
	v_cndmask_b32_e64 v56, 0, v64, s[12:13]
	v_mov_b32_dpp v65, v49 row_ror:1 row_mask:0xf bank_mask:0xf bound_ctrl:1
	v_cndmask_b32_e64 v57, 0, v102, s[12:13]
	v_cndmask_b32_e64 v50, v59, 0, s[10:11]
	v_cndmask_b32_e64 v51, v61, 0, s[10:11]
	v_cndmask_b32_e64 v54, v63, 0, s[10:11]
	v_cndmask_b32_e64 v55, v65, 0, s[10:11]
	v_pk_fma_f32 v[56:57], v[68:69], v[56:57], v[80:81]
	v_pk_fma_f32 v[52:53], v[66:67], v[52:53], v[78:79]
	v_add_u32_e32 v0, s25, v194
	v_pk_fma_f32 v[54:55], v[76:77], v[54:55], v[56:57]
	v_pk_fma_f32 v[50:51], v[74:75], v[50:51], v[52:53]
	v_mul_lo_u32 v58, v0, s16
	v_pk_fma_f32 v[48:49], v[48:49], v[72:73], v[54:55]
	v_pk_fma_f32 v[46:47], v[46:47], v[70:71], v[50:51]
	v_add_u32_e32 v0, v58, v158
	v_pk_mul_f32 v[48:49], v[164:165], v[48:49]
	v_pk_mul_f32 v[46:47], v[166:167], v[46:47]
	s_nop 0
	v_cvt_pk_bf16_f32 v46, v46, v47
	v_cvt_pk_bf16_f32 v47, v48, v49
	v_lshl_add_u64 v[48:49], v[0:1], 1, s[36:37]
	global_store_dwordx2 v[48:49], v[46:47], off
	v_mov_b32_dpp v56, v42 row_ror:2 row_mask:0xf bank_mask:0xf bound_ctrl:1
	v_mov_b32_dpp v0, v42 row_ror:1 row_mask:0xf bank_mask:0xf bound_ctrl:1
	v_cndmask_b32_e64 v50, v60, v56, s[12:13]
	v_mov_b32_dpp v57, v43 row_ror:1 row_mask:0xf bank_mask:0xf bound_ctrl:1
	v_mov_b32_dpp v60, v44 row_ror:1 row_mask:0xf bank_mask:0xf bound_ctrl:1
	v_cndmask_b32_e64 v46, v0, v59, s[10:11]
	v_mov_b32_dpp v59, v43 row_ror:2 row_mask:0xf bank_mask:0xf bound_ctrl:1
	v_cndmask_b32_e64 v47, v57, v61, s[10:11]
	v_mov_b32_dpp v61, v44 row_ror:2 row_mask:0xf bank_mask:0xf bound_ctrl:1
	v_cndmask_b32_e64 v52, v60, v63, s[10:11]
	v_mov_b32_dpp v63, v45 row_ror:2 row_mask:0xf bank_mask:0xf bound_ctrl:1
	v_cndmask_b32_e64 v51, v62, v59, s[12:13]
	v_cndmask_b32_e64 v54, v64, v61, s[12:13]
	v_mov_b32_dpp v62, v45 row_ror:1 row_mask:0xf bank_mask:0xf bound_ctrl:1
	v_cndmask_b32_e64 v55, v102, v63, s[12:13]
	v_cndmask_b32_e64 v53, v62, v65, s[10:11]
	v_pk_fma_f32 v[50:51], v[66:67], v[50:51], v[78:79]
	v_pk_fma_f32 v[54:55], v[68:69], v[54:55], v[80:81]
	v_pk_fma_f32 v[46:47], v[74:75], v[46:47], v[50:51]
	v_pk_fma_f32 v[52:53], v[76:77], v[52:53], v[54:55]
	v_pk_fma_f32 v[42:43], v[42:43], v[70:71], v[46:47]
	v_pk_fma_f32 v[44:45], v[44:45], v[72:73], v[52:53]
	v_pk_mul_f32 v[42:43], v[168:169], v[42:43]
	v_pk_mul_f32 v[44:45], v[170:171], v[44:45]
	v_cvt_pk_bf16_f32 v42, v42, v43
	v_cvt_pk_bf16_f32 v43, v44, v45
	v_add_co_u32_e32 v44, vcc, s0, v48
	s_nop 1
	v_addc_co_u32_e32 v45, vcc, 0, v49, vcc
	global_store_dwordx2 v[44:45], v[42:43], off
	v_mov_b32_dpp v52, v38 row_ror:1 row_mask:0xf bank_mask:0xf bound_ctrl:1
	v_mov_b32_dpp v53, v38 row_ror:2 row_mask:0xf bank_mask:0xf bound_ctrl:1
	v_mov_b32_dpp v54, v39 row_ror:2 row_mask:0xf bank_mask:0xf bound_ctrl:1
	v_cndmask_b32_e64 v42, v52, v0, s[10:11]
	v_cndmask_b32_e64 v44, v56, v53, s[12:13]
	v_mov_b32_dpp v0, v39 row_ror:1 row_mask:0xf bank_mask:0xf bound_ctrl:1
	v_cndmask_b32_e64 v45, v59, v54, s[12:13]
	v_mov_b32_dpp v56, v40 row_ror:2 row_mask:0xf bank_mask:0xf bound_ctrl:1
	v_mov_b32_dpp v59, v41 row_ror:2 row_mask:0xf bank_mask:0xf bound_ctrl:1
	v_cndmask_b32_e64 v43, v0, v57, s[10:11]
	v_mov_b32_dpp v55, v40 row_ror:1 row_mask:0xf bank_mask:0xf bound_ctrl:1
	v_cndmask_b32_e64 v50, v61, v56, s[12:13]
	v_mov_b32_dpp v57, v41 row_ror:1 row_mask:0xf bank_mask:0xf bound_ctrl:1
	v_cndmask_b32_e64 v51, v63, v59, s[12:13]
	v_cndmask_b32_e64 v46, v55, v60, s[10:11]
	v_cndmask_b32_e64 v47, v57, v62, s[10:11]
	v_pk_fma_f32 v[44:45], v[66:67], v[44:45], v[78:79]
	v_pk_fma_f32 v[50:51], v[68:69], v[50:51], v[80:81]
	v_pk_fma_f32 v[42:43], v[74:75], v[42:43], v[44:45]
	v_pk_fma_f32 v[46:47], v[76:77], v[46:47], v[50:51]
	v_pk_fma_f32 v[38:39], v[38:39], v[70:71], v[42:43]
	v_pk_fma_f32 v[40:41], v[40:41], v[72:73], v[46:47]
	v_pk_mul_f32 v[38:39], v[172:173], v[38:39]
	v_pk_mul_f32 v[40:41], v[174:175], v[40:41]
	v_cvt_pk_bf16_f32 v38, v38, v39
	v_cvt_pk_bf16_f32 v39, v40, v41
	v_add_co_u32_e32 v40, vcc, s17, v48
	s_nop 1
	v_addc_co_u32_e32 v41, vcc, 0, v49, vcc
	global_store_dwordx2 v[40:41], v[38:39], off
	v_mov_b32_dpp v39, v30 row_ror:2 row_mask:0xf bank_mask:0xf bound_ctrl:1
	v_cndmask_b32_e64 v40, v53, v39, s[12:13]
	v_mov_b32_dpp v41, v31 row_ror:2 row_mask:0xf bank_mask:0xf bound_ctrl:1
	v_mov_b32_dpp v39, v31 row_ror:1 row_mask:0xf bank_mask:0xf bound_ctrl:1
	v_cndmask_b32_e64 v39, v39, v0, s[10:11]
	v_mov_b32_dpp v0, v32 row_ror:1 row_mask:0xf bank_mask:0xf bound_ctrl:1
	v_mov_b32_dpp v43, v32 row_ror:2 row_mask:0xf bank_mask:0xf bound_ctrl:1
	v_mov_b32_dpp v45, v33 row_ror:2 row_mask:0xf bank_mask:0xf bound_ctrl:1
	v_mov_b32_dpp v38, v30 row_ror:1 row_mask:0xf bank_mask:0xf bound_ctrl:1
	v_cndmask_b32_e64 v41, v54, v41, s[12:13]
	v_cndmask_b32_e64 v42, v0, v55, s[10:11]
	v_cndmask_b32_e64 v44, v56, v43, s[12:13]
	v_mov_b32_dpp v0, v33 row_ror:1 row_mask:0xf bank_mask:0xf bound_ctrl:1
	v_cndmask_b32_e64 v45, v59, v45, s[12:13]
	v_cndmask_b32_e64 v38, v38, v52, s[10:11]
	v_cndmask_b32_e64 v43, v0, v57, s[10:11]
	v_pk_fma_f32 v[40:41], v[66:67], v[40:41], v[78:79]
	v_pk_fma_f32 v[44:45], v[68:69], v[44:45], v[80:81]
	v_pk_fma_f32 v[38:39], v[74:75], v[38:39], v[40:41]
	v_pk_fma_f32 v[42:43], v[76:77], v[42:43], v[44:45]
	v_pk_fma_f32 v[30:31], v[30:31], v[70:71], v[38:39]
	v_pk_fma_f32 v[32:33], v[32:33], v[72:73], v[42:43]
	v_pk_mul_f32 v[30:31], v[132:133], v[30:31]
	v_pk_mul_f32 v[32:33], v[134:135], v[32:33]
	v_cvt_pk_bf16_f32 v30, v30, v31
	v_cvt_pk_bf16_f32 v31, v32, v33
	v_add_co_u32_e32 v32, vcc, s1, v48
	s_nop 1
	v_addc_co_u32_e32 v33, vcc, 0, v49, vcc
	global_store_dwordx2 v[32:33], v[30:31], off
	v_mov_b32_dpp v60, v34 row_ror:2 row_mask:0xf bank_mask:0xf bound_ctrl:1
	v_mov_b32_dpp v62, v35 row_ror:2 row_mask:0xf bank_mask:0xf bound_ctrl:1
	v_mov_b32_dpp v64, v36 row_ror:2 row_mask:0xf bank_mask:0xf bound_ctrl:1
	v_mov_b32_dpp v66, v37 row_ror:2 row_mask:0xf bank_mask:0xf bound_ctrl:1
	v_mov_b32_dpp v59, v34 row_ror:1 row_mask:0xf bank_mask:0xf bound_ctrl:1
	v_mov_b32_dpp v61, v35 row_ror:1 row_mask:0xf bank_mask:0xf bound_ctrl:1
	v_mov_b32_dpp v63, v36 row_ror:1 row_mask:0xf bank_mask:0xf bound_ctrl:1
	v_mov_b32_dpp v65, v37 row_ror:1 row_mask:0xf bank_mask:0xf bound_ctrl:1
	v_cndmask_b32_e64 v52, 0, v60, s[12:13]
	v_cndmask_b32_e64 v53, 0, v62, s[12:13]
	v_cndmask_b32_e64 v56, 0, v64, s[12:13]
	v_cndmask_b32_e64 v57, 0, v66, s[12:13]
	v_cndmask_b32_e64 v50, v59, 0, s[10:11]
	v_cndmask_b32_e64 v51, v61, 0, s[10:11]
	v_cndmask_b32_e64 v54, v63, 0, s[10:11]
	v_cndmask_b32_e64 v55, v65, 0, s[10:11]
	v_add_u32_e32 v0, v114, v178
	s_waitcnt vmcnt(8)
; __device__ __forceinline__ unsigned cvt_pk(float lo, float hi) { f32x2_t v = {lo, hi}; bf16x2_t b = __builtin_convertvector(v, bf16x2_t); return __builtin_bit_cast(unsigned, b); }
; __device__ __forceinline__ f32x4 sigm4(f32x4 v) { f32x4 o; o[0] = sigm(v[0]); o[1] = sigm(v[1]); o[2] = sigm(v[2]); o[3] = sigm(v[3]); return o; }
; __device__ __forceinline__ float dppr1(float x) { return __int_as_float(__builtin_amdgcn_mov_dpp(__float_as_int(x), 0x121, 0xf, 0xf, true)); }
; __device__ __forceinline__ float dppr2(float x) { return __int_as_float(__builtin_amdgcn_mov_dpp(__float_as_int(x), 0x122, 0xf, 0xf, true)); }
;     template <int GV, int NH> __device__ __forceinline__ void part(f32x4 (&acc)[2][2][4][2], const Unit& u, int wr, int wc, int fr, int fq) const {
;     ...
;             for (int m = 0; m < 4; ++m) {
;                 const f32x4 x3 = acc[ai][GV][m][NH];
;                 f32x4 c1, c2, x2, x1;
; #pragma unroll
;                 for (int i = 0; i < 4; ++i) { c1[i] = dppr1(x3[i]); c2[i] = dppr2(x3[i]); x2[i] = f1 ? c1[i] : p1[i]; x1[i] = f2 ? c2[i] : p2[i]; }
;                 p1 = c1; p2 = c2;
;                 const f32x4 o = bb + x1 * w0 + x2 * w1 + x3 * w2;
;                 if (GV == 0) acc[ai][0][m][NH] = o * sigm4(o);
;                 else { const f32x4 r = acc[ai][0][m][NH] * o; u32x2 pk; pk.x = cvt_pk(r[0], r[1]); pk.y = cvt_pk(r[2], r[3]); *(u32x2*)(ACT + rowb + (unsigned)(16 * m) * DFF) = pk; }
	v_pk_fma_f32 v[52:53], v[238:239], v[52:53], v[242:243]
	v_pk_fma_f32 v[56:57], v[240:241], v[56:57], v[244:245]
	v_pk_fma_f32 v[50:51], v[198:199], v[50:51], v[52:53]
	v_pk_fma_f32 v[54:55], v[200:201], v[54:55], v[56:57]
	v_pk_fma_f32 v[34:35], v[34:35], v[202:203], v[50:51]
	v_pk_fma_f32 v[36:37], v[36:37], v[204:205], v[54:55]
	v_pk_mul_f32 v[34:35], v[94:95], v[34:35]
	v_pk_mul_f32 v[36:37], v[96:97], v[36:37]
	v_cvt_pk_bf16_f32 v34, v34, v35
	v_cvt_pk_bf16_f32 v35, v36, v37
	v_lshl_add_u64 v[36:37], v[0:1], 1, s[36:37]
	global_store_dwordx2 v[36:37], v[34:35], off
	v_mov_b32_dpp v56, v26 row_ror:2 row_mask:0xf bank_mask:0xf bound_ctrl:1
	v_mov_b32_dpp v0, v26 row_ror:1 row_mask:0xf bank_mask:0xf bound_ctrl:1
	v_cndmask_b32_e64 v50, v60, v56, s[12:13]
	v_mov_b32_dpp v57, v27 row_ror:1 row_mask:0xf bank_mask:0xf bound_ctrl:1
	v_mov_b32_dpp v60, v28 row_ror:1 row_mask:0xf bank_mask:0xf bound_ctrl:1
	v_cndmask_b32_e64 v34, v0, v59, s[10:11]
	v_mov_b32_dpp v59, v27 row_ror:2 row_mask:0xf bank_mask:0xf bound_ctrl:1
	v_cndmask_b32_e64 v35, v57, v61, s[10:11]
	v_mov_b32_dpp v61, v28 row_ror:2 row_mask:0xf bank_mask:0xf bound_ctrl:1
	v_cndmask_b32_e64 v52, v60, v63, s[10:11]
	v_mov_b32_dpp v63, v29 row_ror:2 row_mask:0xf bank_mask:0xf bound_ctrl:1
	v_cndmask_b32_e64 v51, v62, v59, s[12:13]
	v_cndmask_b32_e64 v54, v64, v61, s[12:13]
	v_mov_b32_dpp v62, v29 row_ror:1 row_mask:0xf bank_mask:0xf bound_ctrl:1
	v_cndmask_b32_e64 v55, v66, v63, s[12:13]
	v_cndmask_b32_e64 v53, v62, v65, s[10:11]
	v_pk_fma_f32 v[54:55], v[240:241], v[54:55], v[244:245]
	v_pk_fma_f32 v[50:51], v[238:239], v[50:51], v[242:243]
	v_pk_fma_f32 v[52:53], v[200:201], v[52:53], v[54:55]
	v_pk_fma_f32 v[34:35], v[198:199], v[34:35], v[50:51]
	v_pk_fma_f32 v[28:29], v[28:29], v[204:205], v[52:53]
	v_pk_fma_f32 v[26:27], v[26:27], v[202:203], v[34:35]
	v_pk_mul_f32 v[28:29], v[90:91], v[28:29]
	v_pk_mul_f32 v[26:27], v[92:93], v[26:27]
	s_nop 0
	v_cvt_pk_bf16_f32 v26, v26, v27
	v_cvt_pk_bf16_f32 v27, v28, v29
	v_add_co_u32_e32 v28, vcc, s0, v36
	s_nop 1
	v_addc_co_u32_e32 v29, vcc, 0, v37, vcc
	global_store_dwordx2 v[28:29], v[26:27], off
	v_mov_b32_dpp v52, v22 row_ror:1 row_mask:0xf bank_mask:0xf bound_ctrl:1
	v_mov_b32_dpp v53, v22 row_ror:2 row_mask:0xf bank_mask:0xf bound_ctrl:1
	v_mov_b32_dpp v54, v23 row_ror:2 row_mask:0xf bank_mask:0xf bound_ctrl:1
	v_cndmask_b32_e64 v26, v52, v0, s[10:11]
	v_cndmask_b32_e64 v28, v56, v53, s[12:13]
	v_mov_b32_dpp v0, v23 row_ror:1 row_mask:0xf bank_mask:0xf bound_ctrl:1
	v_cndmask_b32_e64 v29, v59, v54, s[12:13]
	v_mov_b32_dpp v56, v24 row_ror:2 row_mask:0xf bank_mask:0xf bound_ctrl:1
	v_mov_b32_dpp v59, v25 row_ror:2 row_mask:0xf bank_mask:0xf bound_ctrl:1
	v_cndmask_b32_e64 v27, v0, v57, s[10:11]
	v_mov_b32_dpp v55, v24 row_ror:1 row_mask:0xf bank_mask:0xf bound_ctrl:1
	v_cndmask_b32_e64 v50, v61, v56, s[12:13]
	v_mov_b32_dpp v57, v25 row_ror:1 row_mask:0xf bank_mask:0xf bound_ctrl:1
	v_cndmask_b32_e64 v51, v63, v59, s[12:13]
	v_cndmask_b32_e64 v34, v55, v60, s[10:11]
	v_cndmask_b32_e64 v35, v57, v62, s[10:11]
	v_pk_fma_f32 v[50:51], v[240:241], v[50:51], v[244:245]
	v_pk_fma_f32 v[28:29], v[238:239], v[28:29], v[242:243]
	v_pk_fma_f32 v[34:35], v[200:201], v[34:35], v[50:51]
	v_pk_fma_f32 v[26:27], v[198:199], v[26:27], v[28:29]
	v_pk_fma_f32 v[24:25], v[24:25], v[204:205], v[34:35]
	v_pk_fma_f32 v[22:23], v[22:23], v[202:203], v[26:27]
	v_pk_mul_f32 v[24:25], v[86:87], v[24:25]
	v_pk_mul_f32 v[22:23], v[88:89], v[22:23]
	s_nop 0
	v_cvt_pk_bf16_f32 v22, v22, v23
	v_cvt_pk_bf16_f32 v23, v24, v25
	v_add_co_u32_e32 v24, vcc, s17, v36
	s_nop 1
	v_addc_co_u32_e32 v25, vcc, 0, v37, vcc
	global_store_dwordx2 v[24:25], v[22:23], off
	v_mov_b32_dpp v23, v18 row_ror:2 row_mask:0xf bank_mask:0xf bound_ctrl:1
	v_cndmask_b32_e64 v24, v53, v23, s[12:13]
	v_mov_b32_dpp v25, v19 row_ror:2 row_mask:0xf bank_mask:0xf bound_ctrl:1
	v_mov_b32_dpp v23, v19 row_ror:1 row_mask:0xf bank_mask:0xf bound_ctrl:1
	v_cndmask_b32_e64 v23, v23, v0, s[10:11]
	v_mov_b32_dpp v0, v20 row_ror:1 row_mask:0xf bank_mask:0xf bound_ctrl:1
	v_mov_b32_dpp v27, v20 row_ror:2 row_mask:0xf bank_mask:0xf bound_ctrl:1
	v_mov_b32_dpp v29, v21 row_ror:2 row_mask:0xf bank_mask:0xf bound_ctrl:1
	v_mov_b32_dpp v22, v18 row_ror:1 row_mask:0xf bank_mask:0xf bound_ctrl:1
	v_cndmask_b32_e64 v25, v54, v25, s[12:13]
	v_cndmask_b32_e64 v26, v0, v55, s[10:11]
	v_cndmask_b32_e64 v28, v56, v27, s[12:13]
	v_mov_b32_dpp v0, v21 row_ror:1 row_mask:0xf bank_mask:0xf bound_ctrl:1
	v_cndmask_b32_e64 v29, v59, v29, s[12:13]
	v_cndmask_b32_e64 v22, v22, v52, s[10:11]
	v_cndmask_b32_e64 v27, v0, v57, s[10:11]
	v_pk_fma_f32 v[28:29], v[240:241], v[28:29], v[244:245]
	v_pk_fma_f32 v[24:25], v[238:239], v[24:25], v[242:243]
	v_pk_fma_f32 v[26:27], v[200:201], v[26:27], v[28:29]
	v_pk_fma_f32 v[22:23], v[198:199], v[22:23], v[24:25]
	v_pk_fma_f32 v[20:21], v[20:21], v[204:205], v[26:27]
	v_pk_fma_f32 v[18:19], v[18:19], v[202:203], v[22:23]
	v_pk_mul_f32 v[20:21], v[82:83], v[20:21]
	v_pk_mul_f32 v[18:19], v[84:85], v[18:19]
	s_nop 0
	v_cvt_pk_bf16_f32 v18, v18, v19
	v_cvt_pk_bf16_f32 v19, v20, v21
	v_add_co_u32_e32 v20, vcc, s1, v36
	s_nop 1
	v_addc_co_u32_e32 v21, vcc, 0, v37, vcc
	global_store_dwordx2 v[20:21], v[18:19], off
	v_mov_b32_dpp v27, v14 row_ror:2 row_mask:0xf bank_mask:0xf bound_ctrl:1
	v_mov_b32_dpp v29, v15 row_ror:2 row_mask:0xf bank_mask:0xf bound_ctrl:1
	v_mov_b32_dpp v35, v16 row_ror:2 row_mask:0xf bank_mask:0xf bound_ctrl:1
	v_mov_b32_dpp v37, v17 row_ror:2 row_mask:0xf bank_mask:0xf bound_ctrl:1
	v_mov_b32_dpp v26, v14 row_ror:1 row_mask:0xf bank_mask:0xf bound_ctrl:1
; __device__ __forceinline__ unsigned cvt_pk(float lo, float hi) { f32x2_t v = {lo, hi}; bf16x2_t b = __builtin_convertvector(v, bf16x2_t); return __builtin_bit_cast(unsigned, b); }
; __device__ __forceinline__ f32x4 sigm4(f32x4 v) { f32x4 o; o[0] = sigm(v[0]); o[1] = sigm(v[1]); o[2] = sigm(v[2]); o[3] = sigm(v[3]); return o; }
; #define PG8_BAR __builtin_amdgcn_s_barrier()
; __device__ __forceinline__ float dppr1(float x) { return __int_as_float(__builtin_amdgcn_mov_dpp(__float_as_int(x), 0x121, 0xf, 0xf, true)); }
; __device__ __forceinline__ float dppr2(float x) { return __int_as_float(__builtin_amdgcn_mov_dpp(__float_as_int(x), 0x122, 0xf, 0xf, true)); }
; template <class Epi, class Sched, bool ALIGN_EPI>
; __device__ __forceinline__ void gemm_phase(LAS unsigned char* lds, const int K, const int lda, const int ldb, const Sched& S, const Epi& E) {
;     ...
;         if (!has_next) break;
;         if (!(Epi::KEEP3 && cur.z < 2))
; #pragma unroll
;         for (int a = 0; a < 2; ++a)
; #pragma unroll
;             for (int b = 0; b < 2; ++b)
; #pragma unroll
;                 for (int m = 0; m < 4; ++m)
; #pragma unroll
;                     for (int n = 0; n < 2; ++n) acc[a][b][m][n] = (f32x4){0.f, 0.f, 0.f, 0.f};
;         cur = nxt; cA = nA; cB = nB; ++ui;
;         if constexpr (ALIGN_EPI) { if (wr == 1) PG8_BAR; }
;     template <int GV, int NH> __device__ __forceinline__ void part(f32x4 (&acc)[2][2][4][2], const Unit& u, int wr, int wc, int fr, int fq) const {
;     ...
;             for (int m = 0; m < 4; ++m) {
;                 const f32x4 x3 = acc[ai][GV][m][NH];
;                 f32x4 c1, c2, x2, x1;
; #pragma unroll
;                 for (int i = 0; i < 4; ++i) { c1[i] = dppr1(x3[i]); c2[i] = dppr2(x3[i]); x2[i] = f1 ? c1[i] : p1[i]; x1[i] = f2 ? c2[i] : p2[i]; }
;                 p1 = c1; p2 = c2;
;                 const f32x4 o = bb + x1 * w0 + x2 * w1 + x3 * w2;
;                 if (GV == 0) acc[ai][0][m][NH] = o * sigm4(o);
;                 else { const f32x4 r = acc[ai][0][m][NH] * o; u32x2 pk; pk.x = cvt_pk(r[0], r[1]); pk.y = cvt_pk(r[2], r[3]); *(u32x2*)(ACT + rowb + (unsigned)(16 * m) * DFF) = pk; }
	v_cndmask_b32_e64 v20, 0, v27, s[12:13]
	v_mov_b32_dpp v28, v15 row_ror:1 row_mask:0xf bank_mask:0xf bound_ctrl:1
	v_cndmask_b32_e64 v21, 0, v29, s[12:13]
	v_mov_b32_dpp v34, v16 row_ror:1 row_mask:0xf bank_mask:0xf bound_ctrl:1
	v_cndmask_b32_e64 v24, 0, v35, s[12:13]
	v_mov_b32_dpp v36, v17 row_ror:1 row_mask:0xf bank_mask:0xf bound_ctrl:1
	v_cndmask_b32_e64 v25, 0, v37, s[12:13]
	v_cndmask_b32_e64 v18, v26, 0, s[10:11]
	v_cndmask_b32_e64 v19, v28, 0, s[10:11]
	v_cndmask_b32_e64 v22, v34, 0, s[10:11]
	v_cndmask_b32_e64 v23, v36, 0, s[10:11]
	v_pk_fma_f32 v[20:21], v[238:239], v[20:21], v[242:243]
	v_pk_fma_f32 v[24:25], v[240:241], v[24:25], v[244:245]
	v_pk_fma_f32 v[18:19], v[198:199], v[18:19], v[20:21]
	v_pk_fma_f32 v[22:23], v[200:201], v[22:23], v[24:25]
	v_pk_fma_f32 v[14:15], v[14:15], v[202:203], v[18:19]
	v_pk_fma_f32 v[16:17], v[16:17], v[204:205], v[22:23]
	v_add_u32_e32 v0, v58, v114
	v_pk_mul_f32 v[16:17], v[138:139], v[16:17]
	v_pk_mul_f32 v[14:15], v[136:137], v[14:15]
	s_nop 0
	v_cvt_pk_bf16_f32 v14, v14, v15
	v_cvt_pk_bf16_f32 v15, v16, v17
	v_lshl_add_u64 v[16:17], v[0:1], 1, s[36:37]
	global_store_dwordx2 v[16:17], v[14:15], off
	v_mov_b32_dpp v24, v10 row_ror:2 row_mask:0xf bank_mask:0xf bound_ctrl:1
	v_mov_b32_dpp v0, v10 row_ror:1 row_mask:0xf bank_mask:0xf bound_ctrl:1
	v_cndmask_b32_e64 v18, v27, v24, s[12:13]
	v_mov_b32_dpp v25, v11 row_ror:1 row_mask:0xf bank_mask:0xf bound_ctrl:1
	v_mov_b32_dpp v27, v12 row_ror:1 row_mask:0xf bank_mask:0xf bound_ctrl:1
	v_cndmask_b32_e64 v14, v0, v26, s[10:11]
	v_mov_b32_dpp v26, v11 row_ror:2 row_mask:0xf bank_mask:0xf bound_ctrl:1
	v_cndmask_b32_e64 v15, v25, v28, s[10:11]
	v_mov_b32_dpp v28, v12 row_ror:2 row_mask:0xf bank_mask:0xf bound_ctrl:1
	v_cndmask_b32_e64 v20, v27, v34, s[10:11]
	v_mov_b32_dpp v34, v13 row_ror:2 row_mask:0xf bank_mask:0xf bound_ctrl:1
	v_cndmask_b32_e64 v19, v29, v26, s[12:13]
	v_cndmask_b32_e64 v22, v35, v28, s[12:13]
	v_mov_b32_dpp v29, v13 row_ror:1 row_mask:0xf bank_mask:0xf bound_ctrl:1
	v_cndmask_b32_e64 v23, v37, v34, s[12:13]
	v_cndmask_b32_e64 v21, v29, v36, s[10:11]
	v_pk_fma_f32 v[22:23], v[240:241], v[22:23], v[244:245]
	v_pk_fma_f32 v[18:19], v[238:239], v[18:19], v[242:243]
	v_pk_fma_f32 v[20:21], v[200:201], v[20:21], v[22:23]
	v_pk_fma_f32 v[14:15], v[198:199], v[14:15], v[18:19]
	v_pk_fma_f32 v[12:13], v[12:13], v[204:205], v[20:21]
	v_pk_fma_f32 v[10:11], v[10:11], v[202:203], v[14:15]
	v_pk_mul_f32 v[12:13], v[140:141], v[12:13]
	v_pk_mul_f32 v[10:11], v[142:143], v[10:11]
	s_nop 0
	v_cvt_pk_bf16_f32 v10, v10, v11
	v_cvt_pk_bf16_f32 v11, v12, v13
	v_add_co_u32_e32 v12, vcc, s0, v16
	s_nop 1
	v_addc_co_u32_e32 v13, vcc, 0, v17, vcc
	global_store_dwordx2 v[12:13], v[10:11], off
	v_mov_b32_dpp v20, v6 row_ror:1 row_mask:0xf bank_mask:0xf bound_ctrl:1
	v_mov_b32_dpp v21, v6 row_ror:2 row_mask:0xf bank_mask:0xf bound_ctrl:1
	v_mov_b32_dpp v22, v7 row_ror:2 row_mask:0xf bank_mask:0xf bound_ctrl:1
	v_cndmask_b32_e64 v10, v20, v0, s[10:11]
	v_cndmask_b32_e64 v12, v24, v21, s[12:13]
	v_mov_b32_dpp v0, v7 row_ror:1 row_mask:0xf bank_mask:0xf bound_ctrl:1
	v_cndmask_b32_e64 v13, v26, v22, s[12:13]
	v_mov_b32_dpp v24, v8 row_ror:2 row_mask:0xf bank_mask:0xf bound_ctrl:1
	v_mov_b32_dpp v26, v9 row_ror:2 row_mask:0xf bank_mask:0xf bound_ctrl:1
	v_cndmask_b32_e64 v11, v0, v25, s[10:11]
	v_mov_b32_dpp v23, v8 row_ror:1 row_mask:0xf bank_mask:0xf bound_ctrl:1
	v_cndmask_b32_e64 v18, v28, v24, s[12:13]
	v_mov_b32_dpp v25, v9 row_ror:1 row_mask:0xf bank_mask:0xf bound_ctrl:1
	v_cndmask_b32_e64 v19, v34, v26, s[12:13]
	v_cndmask_b32_e64 v14, v23, v27, s[10:11]
	v_cndmask_b32_e64 v15, v25, v29, s[10:11]
	v_pk_fma_f32 v[18:19], v[240:241], v[18:19], v[244:245]
	v_pk_fma_f32 v[12:13], v[238:239], v[12:13], v[242:243]
	v_pk_fma_f32 v[14:15], v[200:201], v[14:15], v[18:19]
	v_pk_fma_f32 v[10:11], v[198:199], v[10:11], v[12:13]
	v_pk_fma_f32 v[8:9], v[8:9], v[204:205], v[14:15]
	v_pk_fma_f32 v[6:7], v[6:7], v[202:203], v[10:11]
	v_pk_mul_f32 v[8:9], v[144:145], v[8:9]
	v_pk_mul_f32 v[6:7], v[176:177], v[6:7]
	s_nop 0
	v_cvt_pk_bf16_f32 v6, v6, v7
	v_cvt_pk_bf16_f32 v7, v8, v9
	v_add_co_u32_e32 v8, vcc, s17, v16
	s_nop 1
	v_addc_co_u32_e32 v9, vcc, 0, v17, vcc
	global_store_dwordx2 v[8:9], v[6:7], off
	v_mov_b32_dpp v7, v2 row_ror:2 row_mask:0xf bank_mask:0xf bound_ctrl:1
	v_cndmask_b32_e64 v8, v21, v7, s[12:13]
	v_mov_b32_dpp v9, v3 row_ror:2 row_mask:0xf bank_mask:0xf bound_ctrl:1
	v_mov_b32_dpp v7, v3 row_ror:1 row_mask:0xf bank_mask:0xf bound_ctrl:1
	v_cndmask_b32_e64 v7, v7, v0, s[10:11]
	v_mov_b32_dpp v0, v4 row_ror:1 row_mask:0xf bank_mask:0xf bound_ctrl:1
	v_mov_b32_dpp v11, v4 row_ror:2 row_mask:0xf bank_mask:0xf bound_ctrl:1
	v_mov_b32_dpp v13, v5 row_ror:2 row_mask:0xf bank_mask:0xf bound_ctrl:1
	v_mov_b32_dpp v6, v2 row_ror:1 row_mask:0xf bank_mask:0xf bound_ctrl:1
	v_cndmask_b32_e64 v9, v22, v9, s[12:13]
	v_cndmask_b32_e64 v10, v0, v23, s[10:11]
	v_cndmask_b32_e64 v12, v24, v11, s[12:13]
	v_mov_b32_dpp v0, v5 row_ror:1 row_mask:0xf bank_mask:0xf bound_ctrl:1
	v_cndmask_b32_e64 v13, v26, v13, s[12:13]
	v_cndmask_b32_e64 v6, v6, v20, s[10:11]
	v_cndmask_b32_e64 v11, v0, v25, s[10:11]
	v_pk_fma_f32 v[12:13], v[240:241], v[12:13], v[244:245]
	v_pk_fma_f32 v[8:9], v[238:239], v[8:9], v[242:243]
	v_pk_fma_f32 v[10:11], v[200:201], v[10:11], v[12:13]
	v_pk_fma_f32 v[6:7], v[198:199], v[6:7], v[8:9]
	v_pk_fma_f32 v[4:5], v[4:5], v[204:205], v[10:11]
	v_pk_fma_f32 v[2:3], v[2:3], v[202:203], v[6:7]
	v_pk_mul_f32 v[4:5], v[98:99], v[4:5]
	v_pk_mul_f32 v[2:3], v[100:101], v[2:3]
	s_nop 0
	v_cvt_pk_bf16_f32 v2, v2, v3
	v_cvt_pk_bf16_f32 v3, v4, v5
	v_add_co_u32_e32 v4, vcc, 0x42000, v16
	s_nop 1
	v_addc_co_u32_e32 v5, vcc, 0, v17, vcc
	global_store_dwordx2 v[4:5], v[2:3], off
	s_andn2_b64 vcc, exec, s[14:15]
	s_mov_b64 s[14:15], -1
	s_cbranch_vccnz .LBB0_1918
	s_andn2_b64 vcc, exec, s[2:3]
	s_cbranch_vccnz .LBB0_1917
	s_barrier
	s_branch .LBB0_1917
